# hand-scheduled compact rwkv7 scan loops (both variants), ssd tiles prio 3 / rwkv prio 2, ssd tiles moved to blocks 384..431
# speedup vs baseline: 1.0078x; 1.0078x over previous
; __device__ __forceinline__ void phase_mixers(const Params& p, int l, unsigned char* smem) {
;     ...
;   const int bid = blockIdx.x, G = gridDim.x;
;   if (G == 512) {
;     if (bid < 128) {
;       __builtin_amdgcn_s_setprio(3);
;       rwkv_tile<false>(p, l, bid, smem);
;       __builtin_amdgcn_s_setprio(0);
;     } else if (bid < 256) {
;       __builtin_amdgcn_s_setprio(3);
;       rwkv_tile<true>(p, l, bid, smem);
;       __builtin_amdgcn_s_setprio(0);
;     } else if (bid < 304) {
;       __builtin_amdgcn_s_setprio(2);
;       ssd_tile(p, l, bid - 256, smem);
;       __builtin_amdgcn_s_setprio(0);
;     }
.LBB0_8:
	s_cmpk_gt_i32 s97, 0x3e8
	s_cselect_b64 s[2:3], -1, 0
	v_writelane_b32 v252, s2, 16
	s_add_u32 s0, s0, 0x198
	s_addc_u32 s1, s1, 0
	v_writelane_b32 v252, s3, 17
	v_writelane_b32 v252, s0, 18
	v_readlane_b32 s44, v251, 32
	v_readlane_b32 s52, v251, 40
	v_writelane_b32 v252, s1, 19
	s_add_u32 s0, s24, 0x200
	s_addc_u32 s1, s25, 0
	v_writelane_b32 v252, s0, 20
	v_readlane_b32 s53, v251, 41
	v_mov_b32_e32 v188, 0x100
	v_writelane_b32 v252, s1, 21
	s_add_u32 s0, s24, 0x1000
	s_addc_u32 s1, s25, 0
	v_writelane_b32 v252, s0, 22
	v_sub_co_u32_e32 v1, vcc, s93, v188
	s_nop 0
	v_writelane_b32 v252, s1, 23
	s_add_u32 s0, s24, 0x1100
	s_addc_u32 s1, s25, 0
	v_writelane_b32 v252, s0, 24
	s_movk_i32 s33, 0x300
	v_readlane_b32 s4, v251, 48
	v_writelane_b32 v252, s1, 25
	s_add_u32 s0, s24, 0x1200
	s_addc_u32 s1, s25, 0
	v_writelane_b32 v252, s0, 26
	v_readlane_b32 s18, v251, 62
	v_readlane_b32 s19, v251, 63
	v_writelane_b32 v252, s1, 27
	s_add_u32 s0, s24, 0x1300
	s_addc_u32 s1, s25, 0
	v_writelane_b32 v252, s0, 28
	s_cmp_eq_u32 s20, 15
	v_readlane_b32 s6, v251, 50
	v_writelane_b32 v252, s1, 29
	s_cselect_b64 s[0:1], -1, 0
	v_writelane_b32 v252, s0, 30
	s_cmp_eq_u32 s20, 14
	v_readlane_b32 s7, v251, 51
	v_writelane_b32 v252, s1, 31
	s_cselect_b64 s[0:1], -1, 0
	v_writelane_b32 v252, s0, 32
	s_cmp_eq_u32 s20, 13
	v_readlane_b32 s45, v251, 33
	v_writelane_b32 v252, s1, 33
	s_cselect_b64 s[0:1], -1, 0
	v_writelane_b32 v252, s0, 34
	s_cmp_eq_u32 s20, 12
	v_readlane_b32 s46, v251, 34
	v_writelane_b32 v252, s1, 35
	s_cselect_b64 s[0:1], -1, 0
	v_writelane_b32 v252, s0, 36
	s_cmp_eq_u32 s20, 11
	v_readlane_b32 s47, v251, 35
	v_writelane_b32 v252, s1, 37
	s_cselect_b64 s[0:1], -1, 0
	v_writelane_b32 v252, s0, 38
	s_cmp_eq_u32 s20, 10
	v_readlane_b32 s48, v251, 36
	v_writelane_b32 v252, s1, 39
	s_cselect_b64 s[0:1], -1, 0
	v_writelane_b32 v252, s0, 40
	s_cmp_eq_u32 s20, 9
	v_readlane_b32 s49, v251, 37
	v_writelane_b32 v252, s1, 41
	s_cselect_b64 s[0:1], -1, 0
	v_writelane_b32 v252, s0, 42
	s_cmp_eq_u32 s20, 8
	v_readlane_b32 s50, v251, 38
	v_writelane_b32 v252, s1, 43
	s_cselect_b64 s[0:1], -1, 0
	v_writelane_b32 v252, s0, 44
	s_cmp_eq_u32 s20, 7
	v_readlane_b32 s51, v251, 39
	v_writelane_b32 v252, s1, 45
	s_cselect_b64 s[0:1], -1, 0
	v_writelane_b32 v252, s0, 46
	s_cmp_eq_u32 s20, 6
	v_readlane_b32 s36, v251, 0
	v_writelane_b32 v252, s1, 47
	s_cselect_b64 s[0:1], -1, 0
	v_writelane_b32 v252, s0, 48
	s_cmp_eq_u32 s20, 5
	v_readlane_b32 s5, v251, 49
	v_writelane_b32 v252, s1, 49
	s_cselect_b64 s[0:1], -1, 0
	v_writelane_b32 v252, s0, 50
	s_cmp_eq_u32 s20, 4
	v_readlane_b32 s40, v251, 4
	v_writelane_b32 v252, s1, 51
	s_cselect_b64 s[0:1], -1, 0
	v_writelane_b32 v252, s0, 52
	s_cmp_eq_u32 s20, 3
	v_readlane_b32 s41, v251, 5
	v_writelane_b32 v252, s1, 53
	s_cselect_b64 s[0:1], -1, 0
	v_writelane_b32 v252, s0, 54
	s_cmp_eq_u32 s20, 2
	v_readlane_b32 s76, v251, 16
	v_writelane_b32 v252, s1, 55
	s_cselect_b64 s[0:1], -1, 0
	v_writelane_b32 v252, s0, 56
	s_cmp_eq_u32 s20, 1
	v_readlane_b32 s84, v251, 24
	v_writelane_b32 v252, s1, 57
	s_cselect_b64 s[0:1], -1, 0
	v_writelane_b32 v252, s0, 58
	s_cmp_eq_u32 s20, 0
	v_readlane_b32 s85, v251, 25
	v_writelane_b32 v252, s1, 59
	s_cselect_b64 s[0:1], -1, 0
	v_writelane_b32 v252, s0, 60
	v_readlane_b32 s86, v251, 26
	v_readlane_b32 s87, v251, 27
	v_writelane_b32 v252, s1, 61
	s_lshl_b32 s0, s20, 8
	s_add_u32 s0, s24, s0
	s_addc_u32 s1, s25, 0
	s_add_u32 s2, s0, 0x1400
	s_addc_u32 s3, s1, 0
	s_add_u32 s0, s0, 0x2400
	s_addc_u32 s1, s1, 0
	v_writelane_b32 v253, s0, 0
	v_writelane_b32 v252, s2, 62
	v_readfirstlane_b32 s20, v1
	s_sub_i32 s20, s93, 0x180
	v_writelane_b32 v253, s1, 1
	s_add_u32 s0, s24, 0x3400
	s_addc_u32 s1, s25, 0
	v_writelane_b32 v253, s0, 2
	v_writelane_b32 v252, s3, 63
	v_readlane_b32 s77, v251, 17
	v_writelane_b32 v253, s1, 3
	s_add_u32 s0, s24, 0x3500
	s_addc_u32 s1, s25, 0
	v_writelane_b32 v253, s0, 4
	s_cmpk_lt_i32 s93, 0x1000
	v_readlane_b32 s14, v251, 58
	v_writelane_b32 v253, s1, 5
	s_cselect_b64 s[0:1], -1, 0
	v_writelane_b32 v253, s0, 6
	s_cmp_eq_u32 s93, 0
	v_readlane_b32 s15, v251, 59
	v_writelane_b32 v253, s1, 7
	s_cselect_b64 s[0:1], -1, 0
	v_writelane_b32 v253, s0, 8
	s_cmpk_lt_i32 s93, 0x471
	v_readlane_b32 s37, v251, 1
	v_writelane_b32 v253, s1, 9
	s_cselect_b64 s[0:1], -1, 0
	v_writelane_b32 v253, s0, 10
	s_cmpk_lt_i32 s93, 0x1100
	v_readlane_b32 s8, v251, 52
	v_writelane_b32 v253, s1, 11
	s_cselect_b64 s[0:1], -1, 0
	v_writelane_b32 v253, s0, 12
	s_cmpk_lt_i32 s93, 0x3a0
	v_readlane_b32 s9, v251, 53
	v_writelane_b32 v253, s1, 13
	s_cselect_b64 s[0:1], -1, 0
	v_writelane_b32 v253, s0, 14
	s_cmpk_lt_i32 s93, 0x5a0
	v_readlane_b32 s10, v251, 54
	v_writelane_b32 v253, s1, 15
	s_cselect_b64 s[0:1], -1, 0
	v_writelane_b32 v253, s0, 16
	v_readlane_b32 s11, v251, 55
	v_readlane_b32 s54, v251, 42
	v_writelane_b32 v253, s1, 17
	s_add_u32 s0, s74, 0xe0c000
	s_addc_u32 s1, s75, 0
	v_writelane_b32 v253, s0, 18
	s_add_u32 s92, s52, 0x740000
	v_readlane_b32 s55, v251, 43
	v_writelane_b32 v253, s1, 19
	s_addc_u32 s0, s53, 0
	s_cmpk_lt_i32 s93, 0x2a8
	v_writelane_b32 v253, s0, 20
	s_cselect_b64 s[0:1], -1, 0
	v_writelane_b32 v253, s0, 21
	s_cmpk_gt_i32 s93, 0x7f
	s_mov_b32 s29, 0
	v_writelane_b32 v253, s1, 22
	s_cselect_b64 s[0:1], -1, 0
	v_writelane_b32 v253, s0, 23
	v_readlane_b32 s44, v251, 8
	v_readlane_b32 s45, v251, 9
	v_writelane_b32 v253, s1, 24
	s_xor_b64 s[0:1], vcc, -1
	v_writelane_b32 v253, s0, 25
	s_sub_i32 s0, s93, 0x180
	s_cmp_lt_u32 s0, 48
	v_readlane_b32 s48, v251, 12
	v_writelane_b32 v253, s1, 26
	s_cselect_b64 s[0:1], -1, 0
	v_writelane_b32 v253, s0, 27
	v_readlane_b32 s49, v251, 13
; template <bool DUAL>
; __device__ __forceinline__ void rwkv_tile(const Params& p, int l, int tile, unsigned char* smem) {
;   const int part = tile >> 7;
;   const int rg = tile & 3, h = (tile >> 2) & 3, b = (tile >> 4) & 3, d = (tile >> 6) & 1;
;   const int cbeg = (part == 0) ? 0 : CSPLIT, cend = (part == 0) ? CSPLIT : 136;
;   bf16_t* raw = (bf16_t*)smem;
;   bf16_t* pre = raw + 34 * 192;
;   float* rec = (float*)(smem + 13056 + 12288);
;   const int tid = launder(threadIdx.x), lane = tid & 63, w = tid >> 6, fr = lane & 15, fq = lane >> 4;
;   const int row = rg * 16 + w * 4 + fq;
;   const int c0 = fr * 4;
;   const int ld2 = l * 2 + d;
;   const size_t rowbase = (size_t)b * TPB;
;   const int lc = (tid & 15) * 4;
;   const float* mu0 = p.rwkv_mu + (size_t)(l * 2 + 0) * 1024 + h * 64 + lc;
;   const float* mu1 = p.rwkv_mu + (size_t)(l * 2 + 1) * 1024 + h * 64 + lc;
;   const float4 m0r = *(const float4*)mu0, m1r = *(const float4*)mu1;
;   const float4 m0k = *(const float4*)(mu0 + 256), m1k = *(const float4*)(mu1 + 256);
;   const float4 m0v = *(const float4*)(mu0 + 512), m1v = *(const float4*)(mu1 + 512);
;   const float4 ka4 = *(const float4*)(p.rwkv_k_a + ld2 * 256 + h * 64 + lc);
;   v2f sA = {0.f, 0.f}, sB = {0.f, 0.f};
; __device__ __forceinline__ void ssd_tile(const Params& p, int l, int tile, unsigned char* smem) {
;   const int h = tile % 6, b = (tile / 6) & 3, d = tile / 24, g = h / 3;
;   bf16_t* Cs0 = (bf16_t*)smem;
;   bf16_t* Bs = Cs0 + 2 * 32 * 136;
;   bf16_t* Xs = Bs + 32 * 136;
;   bf16_t* BtT = Xs + 32 * 72;
;   bf16_t* XdT = BtT + 128 * 40;
;   bf16_t* Ms = XdT + 64 * 40;
;   bf16_t* Sb = Ms + 32 * 40;
;   float* dc = (float*)(Sb + 64 * 136);
;   const int tid = launder(threadIdx.x), lane = tid & 63, w = tid >> 6, fr = lane & 15, fq = lane >> 4;
;   const size_t rowbase = (size_t)b * TPB;
;   f32x4 S[4][2];
; #pragma unroll
;   for (int i = 0; i < 4; ++i)
; #pragma unroll
;     for (int j = 0; j < 2; ++j) S[i][j] = (f32x4){0.f, 0.f, 0.f, 0.f};
;   const int pcc = tid % 40, prow = tid / 40;
;   const bool pact = tid < 240;
;   const int pcol = (pcc < 16) ? (640 + g * 128 + pcc * 8) : ((pcc < 32) ? (384 + g * 128 + (pcc - 16) * 8) : (h * 64 + (pcc - 32) * 8));
;   const bf16_t* pbase = p.PS + rowbase * 912 + pcol;
;   const float2* dbase = p.DTC + (size_t)(d * 6 + h) * TOK + rowbase;
	v_readlane_b32 s56, v251, 44
	v_writelane_b32 v253, s1, 28
	s_sub_i32 s0, s93, 0x180
	s_mov_b32 s3, s0
	s_mulk_i32 s0, 0xab
	s_lshr_b32 s1, s0, 10
	s_mul_i32 s1, s1, 6
	s_sub_i32 s1, s3, s1
	s_and_b32 s3, s1, 0xff
	s_bfe_u32 s2, s0, 0x2000a
	s_lshl_b32 s0, s3, 6
	s_addk_i32 s0, 0xff00
	v_writelane_b32 v253, s0, 29
	s_cmp_gt_u32 s3, 2
	s_movk_i32 s0, 0x180
	s_cselect_b32 s0, s0, 0x100
	v_writelane_b32 v253, s0, 30
	s_cselect_b32 s0, s33, 0x280
	v_writelane_b32 v253, s0, 31
	s_mul_i32 s0, s2, 0x792000
	s_add_u32 s0, s18, s0
	s_addc_u32 s1, s19, 0
	v_writelane_b32 v253, s0, 32
	s_cmp_lt_u32 s20, 24
	v_readlane_b32 s57, v251, 45
	v_writelane_b32 v253, s1, 33
	s_cselect_b64 s[0:1], -1, 0
	v_writelane_b32 v253, s0, 34
	v_readlane_b32 s58, v251, 46
	v_readlane_b32 s59, v251, 47
	v_writelane_b32 v253, s1, 35
	v_writelane_b32 v253, s60, 36
	s_and_b64 s[0:1], s[0:1], exec
	s_movk_i32 s0, 0x10e0
	v_writelane_b32 v253, s61, 37
	v_writelane_b32 v253, s62, 38
	v_writelane_b32 v253, s63, 39
	v_writelane_b32 v253, s64, 40
	v_writelane_b32 v253, s65, 41
	v_writelane_b32 v253, s66, 42
	v_writelane_b32 v253, s67, 43
	v_writelane_b32 v253, s68, 44
	v_writelane_b32 v253, s69, 45
	v_writelane_b32 v253, s70, 46
	v_writelane_b32 v253, s71, 47
	v_writelane_b32 v253, s72, 48
	s_cselect_b32 s4, 0, 0xe0
	s_cselect_b32 s0, s0, 0x100
	s_cmp_gt_u32 s20, 23
	v_writelane_b32 v253, s73, 49
	s_mul_i32 s1, s2, 0x1100
	s_cselect_b32 s2, 6, 0
	v_writelane_b32 v253, s74, 50
	s_cselect_b32 s20, 0x4400, 0
	s_add_i32 s2, s2, s3
	v_writelane_b32 v253, s75, 51
	v_readlane_b32 s60, v252, 0
	s_mul_i32 s2, s2, 0x22000
	v_readlane_b32 s68, v252, 8
	v_readlane_b32 s69, v252, 9
	s_add_u32 s2, s68, s2
	s_addc_u32 s21, s69, 0
	s_lshl_b32 s22, s1, 3
	s_add_u32 s6, s2, s22
	s_addc_u32 s7, s21, 0
	v_writelane_b32 v253, s6, 52
	s_or_b32 s2, s4, 6
	v_readlane_b32 s62, v252, 2
	v_writelane_b32 v253, s7, 53
	v_writelane_b32 v253, s2, 54
	s_or_b32 s2, s4, 12
	v_writelane_b32 v253, s2, 55
	s_or_b32 s2, s4, 18
	v_writelane_b32 v253, s2, 56
	s_or_b32 s2, s4, 24
	v_writelane_b32 v253, s2, 57
	s_add_i32 s6, s1, s20
	s_lshl_b32 s1, s3, 7
	v_writelane_b32 v253, s4, 58
	s_or_b32 s2, s4, 30
	v_readlane_b32 s63, v252, 3
	v_writelane_b32 v253, s2, 59
	s_add_u32 s2, s62, s1
	s_addc_u32 s3, s63, 0
	v_writelane_b32 v253, s2, 60
	s_bfe_u32 s1, s93, 0x20004
	s_lshr_b32 s21, s93, 6
	v_writelane_b32 v253, s3, 61
	s_lshl_b32 s2, s93, 4
	s_and_b32 s3, s2, 48
	v_writelane_b32 v253, s3, 62
	v_writelane_b32 v253, s2, 63
	s_and_b32 s2, s2, 0xc0
	s_bfe_u32 s4, s93, 0x10006
	s_lshl_b32 s3, s2, 2
	s_add_u32 s5, s40, s3
	v_writelane_b32 v254, s5, 0
	s_addc_u32 s5, s41, 0
	v_writelane_b32 v254, s5, 1
	v_writelane_b32 v254, s24, 2
	s_add_u32 s3, s76, s3
	s_mul_i32 s20, s1, 0x1100
	v_writelane_b32 v254, s25, 3
	v_writelane_b32 v254, s26, 4
	v_writelane_b32 v254, s27, 5
	v_readlane_b32 s64, v252, 4
	v_readlane_b32 s84, v254, 2
	v_readlane_b32 s85, v254, 3
	v_readlane_b32 s86, v254, 4
	v_readlane_b32 s87, v254, 5
	v_writelane_b32 v254, s3, 6
	s_addc_u32 s3, s77, 0
	v_writelane_b32 v254, s3, 7
	s_lshl_b32 s3, s20, 11
	s_add_u32 s22, s14, s3
	s_addc_u32 s23, s15, 0
	s_lshl_b32 s24, s2, 1
	s_add_u32 s2, s22, s24
	s_addc_u32 s3, s23, 0
	v_writelane_b32 v254, s2, 8
	v_readlane_b32 s65, v252, 5
	s_movk_i32 s5, 0x10ff
	v_writelane_b32 v254, s3, 9
	s_lshl_b32 s2, s20, 10
	s_add_u32 s2, s64, s2
	s_addc_u32 s3, s65, 0
	s_lshl_b32 s25, s4, 9
	s_add_u32 s25, s2, s25
	s_addc_u32 s26, s3, 0
	s_add_u32 s2, s25, s24
	s_addc_u32 s3, s26, 0
	v_writelane_b32 v254, s2, 10
	s_cmpk_lt_u32 s93, 0x80
	v_readlane_b32 s61, v252, 1
	v_writelane_b32 v254, s3, 11
	s_cselect_b64 s[2:3], -1, 0
	v_writelane_b32 v254, s2, 12
	v_readlane_b32 s70, v252, 10
	v_readlane_b32 s71, v252, 11
	v_writelane_b32 v254, s3, 13
	s_and_b64 s[2:3], s[2:3], exec
	s_movk_i32 s2, 0x88
	s_cselect_b32 s2, 0x4e, s2
	s_cselect_b32 s3, 0, 0x4e
	v_writelane_b32 v254, s2, 14
	s_movk_i32 s2, 0x11e0
	s_cselect_b32 s5, 0xff, s5
	s_cselect_b32 s2, 0xe0, s2
	v_writelane_b32 v254, s5, 15
	s_cselect_b32 s5, 0, 0x100
	s_lshl_b32 s27, s3, 5
	s_sub_i32 s28, s2, s27
	s_cmp_eq_u32 s4, 0
	v_writelane_b32 v254, s5, 16
	s_cselect_b64 s[36:37], -1, 0
	v_writelane_b32 v254, s3, 17
	s_and_b64 s[2:3], s[36:37], exec
	s_movk_i32 s2, 0x9c0
	s_cselect_b32 s3, s2, 0x820
	s_mul_i32 s2, s4, 0x4400
	s_cselect_b32 s5, s27, s28
	s_add_i32 s20, s2, s20
	v_writelane_b32 v254, s4, 18
	s_lshl_b32 s2, s4, 2
	s_or_b32 s2, s2, s1
	v_writelane_b32 v254, s3, 19
	s_add_i32 s3, s3, -1
	s_add_u32 s8, s60, s24
	v_writelane_b32 v254, s3, 20
	s_addc_u32 s9, s61, 0
	v_writelane_b32 v254, s8, 21
	s_mulk_i32 s2, 0x740
	s_mov_b32 s7, s29
	v_writelane_b32 v254, s9, 22
	s_add_u32 s8, s70, s24
	s_addc_u32 s9, s71, 0
	s_bfe_u32 s3, s93, 0x20002
	v_writelane_b32 v254, s8, 23
	s_lshl_b32 s24, s3, 8
	s_add_u32 s4, s40, s24
	v_writelane_b32 v254, s9, 24
	v_writelane_b32 v254, s4, 25
	s_addc_u32 s4, s41, 0
	v_writelane_b32 v254, s4, 26
	s_add_u32 s4, s76, s24
	v_writelane_b32 v254, s4, 27
	s_addc_u32 s4, s77, 0
	s_lshl_b32 s24, s3, 7
	s_add_u32 s8, s22, s24
	v_writelane_b32 v254, s4, 28
	s_addc_u32 s9, s23, 0
	v_writelane_b32 v254, s8, 29
	v_and_b32_e32 v189, 0x3ff, v0
	v_and_b32_e32 v0, 0x3fffffff, v0
	v_writelane_b32 v254, s9, 30
	s_add_u32 s8, s25, s24
	s_addc_u32 s9, s26, 0
	v_writelane_b32 v254, s8, 31
	s_add_i32 s4, s5, -1
	v_mbcnt_lo_u32_b32 v1, -1, 0
	v_writelane_b32 v254, s9, 32
	v_writelane_b32 v254, s5, 33
	v_writelane_b32 v254, s4, 34
	s_add_u32 s4, s60, s24
	s_addc_u32 s5, s61, 0
	s_lshl_b32 s21, s21, 4
	s_lshl_b32 s1, s1, 2
	s_or_b32 s1, s1, s21
	v_writelane_b32 v254, s4, 35
	s_or_b32 s1, s1, s3
	s_lshl_b32 s1, s1, 6
; #define LAS __attribute__((address_space(3)))
; __device__ void sincos_d(double x, float& c, float& s) {
;   double n = rint(x * 0.63661977236758134308);
;   double r = x - n * 1.57079632679489661923;
;   double r2 = r * r;
;   double sn = r * (1.0 + r2 * (-1.0 / 6 + r2 * (1.0 / 120 + r2 * (-1.0 / 5040 + r2 * (1.0 / 362880 + r2 * (-1.0 / 39916800 + r2 * (1.0 / 6227020800.0)))))));
;   double cs = 1.0 + r2 * (-0.5 + r2 * (1.0 / 24 + r2 * (-1.0 / 720 + r2 * (1.0 / 40320 + r2 * (-1.0 / 3628800 + r2 * (1.0 / 479001600.0 + r2 * (-1.0 / 87178291200.0)))))));
; __global__ void __launch_bounds__(NTHREADS, LBW) mega(Params p, int ph_lo, int ph_hi) {
;   extern __shared__ __attribute__((aligned(16))) unsigned char smem[];
;   volatile LAS unsigned* xst = (volatile LAS unsigned*)(smem + LDS_BYTES - 16);
;   XcdBarrier xb;
;   xb.bar = p.bar; xb.x = 0; xb.st = xst;
;   if (ph_hi - ph_lo > 1) {
;     if (threadIdx.x == 0) { xst[0] = 0u; xst[1] = 0u; }
;     __syncthreads();
;     xb = xcd_barrier_post(p.bar, xst);
;   }
	v_writelane_b32 v254, s5, 36
	v_writelane_b32 v254, s2, 37
	s_cmpk_lt_i32 s93, 0x860
	v_writelane_b32 v254, s1, 38
	s_cselect_b64 s[2:3], -1, 0
	v_writelane_b32 v254, s2, 39
	s_cmpk_lt_i32 s93, 0xcc0
	v_readlane_b32 s66, v252, 6
	v_writelane_b32 v254, s3, 40
	s_cselect_b64 s[2:3], -1, 0
	v_writelane_b32 v254, s2, 41
	s_cmpk_lt_i32 s93, 0x600
	v_readlane_b32 s67, v252, 7
	v_writelane_b32 v254, s3, 42
	s_cselect_b64 s[2:3], -1, 0
	v_writelane_b32 v254, s2, 43
	s_cmpk_lt_i32 s93, 0xc0
	v_readlane_b32 s72, v252, 12
	v_writelane_b32 v254, s3, 44
	s_cselect_b64 s[2:3], -1, 0
	v_writelane_b32 v254, s2, 45
	s_cmpk_lt_i32 s93, 0x440
	v_readlane_b32 s73, v252, 13
	v_writelane_b32 v254, s3, 46
	s_cselect_b64 s[2:3], -1, 0
	s_and_b32 s1, s93, 7
	v_writelane_b32 v254, s2, 47
	s_cmpk_lt_u32 s93, 0x440
	v_readlane_b32 s74, v252, 14
	v_writelane_b32 v254, s3, 48
	s_cselect_b64 s[2:3], -1, 0
	v_writelane_b32 v254, s2, 49
	v_readlane_b32 s75, v252, 15
	v_mbcnt_hi_u32_b32 v192, -1, v1
	v_writelane_b32 v254, s3, 50
	s_lshr_b32 s2, s93, 3
	s_lshl_b32 s3, s93, 2
	s_add_u32 s4, s10, 0x80
	v_writelane_b32 v254, s3, 51
	s_addc_u32 s5, s11, 0
	v_writelane_b32 v254, s4, 52
	s_add_u32 s3, s52, 0x80
	v_readlane_b32 s16, v251, 60
	v_writelane_b32 v254, s5, 53
	v_writelane_b32 v254, s3, 54
	s_addc_u32 s3, s53, 0
	s_add_u32 s4, s10, 64
	v_writelane_b32 v254, s3, 55
	s_addc_u32 s5, s11, 0
	v_writelane_b32 v254, s4, 56
	s_add_u32 s3, s52, 64
	v_readlane_b32 s17, v251, 61
	v_writelane_b32 v254, s5, 57
	v_writelane_b32 v254, s3, 58
	s_addc_u32 s3, s53, 0
	v_writelane_b32 v254, s3, 59
	s_add_u32 s3, s54, 0x80
	v_writelane_b32 v254, s3, 60
	s_addc_u32 s3, s55, 0
	v_writelane_b32 v254, s3, 61
	v_writelane_b32 v254, s6, 62
	s_add_i32 s0, s6, s0
	v_writelane_b32 v255, s0, 0
	s_mov_b32 s0, s44
	v_writelane_b32 v255, s0, 1
	s_mov_b32 s0, s45
	v_writelane_b32 v255, s0, 2
	s_mov_b32 s0, s44
	v_writelane_b32 v255, s0, 3
	s_mov_b32 s0, s45
	v_writelane_b32 v255, s0, 4
	s_mov_b32 s0, s48
	v_writelane_b32 v255, s0, 5
	s_mov_b32 s0, s49
	v_writelane_b32 v255, s0, 6
	s_mov_b32 s0, s48
	v_writelane_b32 v255, s0, 7
	s_mov_b32 s0, s49
	v_writelane_b32 v255, s0, 8
	s_mov_b32 s0, s56
	v_writelane_b32 v255, s0, 9
	s_mov_b32 s0, s57
	v_writelane_b32 v255, s0, 10
	s_mov_b32 s0, s56
	v_writelane_b32 v255, s0, 11
	s_mov_b32 s0, s57
	v_writelane_b32 v255, s0, 12
	s_mov_b32 s0, s58
	v_writelane_b32 v255, s0, 13
	s_mov_b32 s0, s59
	v_writelane_b32 v255, s0, 14
	s_mov_b32 s0, s58
	v_writelane_b32 v255, s0, 15
	s_mov_b32 s0, s59
	v_writelane_b32 v255, s0, 16
	s_lshl_b32 s0, s93, 7
	v_writelane_b32 v255, s0, 17
	v_writelane_b32 v255, s1, 18
	s_lshl_b32 s0, s1, 7
	v_writelane_b32 v255, s0, 19
	v_writelane_b32 v255, s2, 20
	s_lshl_b32 s0, s2, 7
	v_writelane_b32 v255, s0, 21
	s_add_i32 s0, 0, 0x12bf0
	v_writelane_b32 v255, s0, 22
	s_add_i32 s0, 0, 0x12bf4
	v_writelane_b32 v255, s0, 23
	s_add_i32 s0, 0, 0x103fc
	v_writelane_b32 v255, s0, 24
	s_add_i32 s0, 0, 0x10380
	v_writelane_b32 v255, s0, 25
	s_add_i32 s0, 0, 0x6e00
	v_writelane_b32 v255, s0, 26
	s_add_i32 s0, 0, 0x6900
	v_writelane_b32 v255, s0, 27
	s_add_i32 s0, 0, 0x12000
	v_writelane_b32 v255, s0, 28
	s_add_i32 s0, 0, 0x700
	v_writelane_b32 v255, s0, 29
	s_add_i32 s0, 0, 0x6600
	v_writelane_b32 v255, s0, 30
	v_cmp_eq_u32_e64 s[2:3], 0, v0
	s_mov_b32 s0, s96
	v_readlane_b32 s38, v251, 2
	v_writelane_b32 v255, s2, 31
	v_readlane_b32 s39, v251, 3
	v_readlane_b32 s88, v251, 28
	v_writelane_b32 v255, s3, 32
	v_cmp_eq_u32_e64 s[2:3], 0, v189
	v_readlane_b32 s89, v251, 29
	v_readlane_b32 s90, v251, 30
	v_writelane_b32 v255, s2, 33
	v_readlane_b32 s91, v251, 31
	v_readlane_b32 s60, v253, 36
	v_writelane_b32 v255, s3, 34
	v_writelane_b32 v255, s96, 35
	v_and_b32_e32 v1, 64, v192
	v_readlane_b32 s62, v253, 38
	v_writelane_b32 v255, s97, 36
	v_writelane_b32 v255, s92, 37
	v_readlane_b32 s63, v253, 39
	s_mov_b32 s21, s29
	v_mov_b32_e32 v164, 0
	v_mov_b32_e32 v190, 1
	v_mov_b32_e32 v191, 0x358637bd
	v_add_u32_e32 v193, 64, v1
	v_xor_b32_e32 v194, 32, v192
	v_xor_b32_e32 v195, 16, v192
	v_xor_b32_e32 v196, 8, v192
	v_xor_b32_e32 v197, 4, v192
	v_xor_b32_e32 v198, 2, v192
	v_xor_b32_e32 v199, 1, v192
	v_mov_b32_e32 v200, 0x10ff
	v_mov_b32_e32 v201, 0xff
	v_mov_b32_e32 v166, 0x3727c5ac
	v_mov_b32_e32 v167, 0x3a27c5ac
	v_mov_b32_e32 v202, 0x740
	v_mov_b32_e32 v203, 0x11ff
	v_mov_b32_e32 v204, 0x80
	v_mov_b32_e32 v205, 0xff800000
	v_writelane_b32 v254, s7, 63
	v_mov_b32_e32 v206, 0x41b17218
	v_mov_b32_e32 v207, 0x7f
	v_mov_b32_e32 v208, 0xf500
	v_mov_b32_e32 v209, 0x420
	v_mov_b32_e32 v210, 0x1ef0
	v_mov_b32_e32 v211, 0x2100
	v_mov_b32_e32 v212, 0x2310
	v_mov_b32_e32 v213, 0x2520
	v_mov_b32_e32 v214, 0x42800000
	v_not_b32_e32 v215, 63
	v_mov_b32_e32 v168, 0x67f544e4
	v_mov_b32_e32 v169, 0xbe5ae645
	v_mov_b32_e32 v170, 0xa556c734
	v_mov_b32_e32 v171, 0x3ec71de3
	v_mov_b32_e32 v172, 0x1a01a01a
	v_mov_b32_e32 v173, 0xbf2a01a0
	v_mov_b32_e32 v174, 0x11111111
	v_mov_b32_e32 v175, 0x3f811111
	v_mov_b32_e32 v176, 0x55555555
	v_mov_b32_e32 v177, 0xbfc55555
	v_mov_b32_e32 v178, 0xeff8d898
	v_mov_b32_e32 v179, 0x3e21eed8
	v_mov_b32_e32 v180, 0xb7789f5c
	v_mov_b32_e32 v181, 0xbe927e4f
	v_mov_b32_e32 v183, 0x3efa01a0
	v_mov_b32_e32 v184, 0x16c16c17
	v_mov_b32_e32 v185, 0xbf56c16c
	v_mov_b32_e32 v187, 0x3fa55555
	s_movk_i32 s31, 0x1000
	s_movk_i32 s40, 0xff
	s_mov_b32 s27, 0x10000
	s_mov_b32 s38, 0x78787879
	s_movk_i32 s39, 0x720
	s_movk_i32 s34, 0x104
	s_movk_i32 s35, 0x3830
	s_movk_i32 s41, 0x3000
	s_mov_b32 s26, 0x20000
	s_mov_b32 s90, 0x30000
	s_mov_b32 s91, 0x40000
	s_mov_b32 s88, 0x60000
	s_movk_i32 s89, 0xfefe
	s_mov_b64 s[22:23], 0x1100
	s_mov_b64 s[16:17], 0x20100
	s_mov_b64 s[24:25], 0x40100
	s_mov_b64 s[18:19], 0x60100
	s_mov_b32 s30, 0x3e000000
	v_writelane_b32 v255, s93, 38
	v_readlane_b32 s12, v251, 56
	v_readlane_b32 s13, v251, 57
	v_readlane_b32 s42, v251, 6
	v_readlane_b32 s43, v251, 7
	v_readlane_b32 s46, v251, 10
	v_readlane_b32 s47, v251, 11
	v_readlane_b32 s50, v251, 14
	v_readlane_b32 s51, v251, 15
	v_readlane_b32 s78, v251, 18
	v_readlane_b32 s79, v251, 19
	v_readlane_b32 s80, v251, 20
	v_readlane_b32 s81, v251, 21
	v_readlane_b32 s82, v251, 22
	v_readlane_b32 s83, v251, 23
	v_readlane_b32 s61, v253, 37
	v_readlane_b32 s64, v253, 40
	v_readlane_b32 s65, v253, 41
	v_readlane_b32 s66, v253, 42
	v_readlane_b32 s67, v253, 43
	v_readlane_b32 s68, v253, 44
	v_readlane_b32 s69, v253, 45
	v_readlane_b32 s70, v253, 46
	v_readlane_b32 s71, v253, 47
	v_readlane_b32 s72, v253, 48
	v_readlane_b32 s73, v253, 49
	v_readlane_b32 s74, v253, 50
	v_readlane_b32 s75, v253, 51
	s_branch .LBB0_11

; __device__ __forceinline__ void ssd_tile(const Params& p, int l, int tile, unsigned char* smem) {
;     ...
;   const int pcc = tid % 40, prow = tid / 40;
;   const bool pact = tid < 240;
;   const int pcol = (pcc < 16) ? (640 + g * 128 + pcc * 8) : ((pcc < 32) ? (384 + g * 128 + (pcc - 16) * 8) : (h * 64 + (pcc - 32) * 8));
; __device__ __forceinline__ void phase_mixers(const Params& p, int l, unsigned char* smem) {
;     ...
;     } else if (bid < 304) {
;       __builtin_amdgcn_s_setprio(2);
;       ssd_tile(p, l, bid - 256, smem);
;       __builtin_amdgcn_s_setprio(0);
.LBB0_434:
	s_and_b64 vcc, exec, s[42:43]
	s_cbranch_vccz .LBB0_590
	v_readlane_b32 s0, v253, 23
	v_readlane_b32 s1, v253, 24
	s_and_b64 vcc, exec, s[0:1]
	s_cbranch_vccz .LBB0_500
	v_readlane_b32 s0, v253, 25
	v_readlane_b32 s1, v253, 26
	v_readlane_b32 s74, v253, 18
	s_and_b64 vcc, exec, s[0:1]
	v_readlane_b32 s75, v253, 19
	v_readlane_b32 s76, v253, 20
	s_cbranch_vccz .LBB0_1383
	v_readlane_b32 s0, v253, 27
	v_readlane_b32 s1, v253, 28
	s_mov_b64 s[58:59], 0
	s_and_b64 vcc, exec, s[0:1]
	s_mov_b64 s[42:43], 0
	s_cbranch_vccz .LBB0_1384
	s_setprio 3
	v_mov_b32_e32 v86, v189
	s_mov_b32 s0, 0x66666667
	s_nop 0
	v_mul_hi_i32 v0, v86, s0
	v_lshrrev_b32_e32 v1, 31, v0
	v_ashrrev_i32_e32 v0, 4, v0
	v_add_u32_e32 v87, v0, v1
	v_mul_lo_u32 v0, v87, 40
	v_sub_u32_e32 v24, v86, v0
	v_cmp_gt_i32_e32 vcc, 16, v24
	v_cmp_lt_i32_e64 s[48:49], 15, v24
	s_and_saveexec_b64 s[42:43], s[48:49]
	s_xor_b64 s[44:45], exec, s[42:43]
	s_cbranch_execz .LBB0_444
	v_cmp_lt_u32_e64 s[42:43], 31, v24
	v_lshlrev_b32_e32 v1, 3, v24
	s_and_saveexec_b64 s[46:47], s[42:43]
	s_xor_b64 s[42:43], exec, s[46:47]
	s_cbranch_execz .LBB0_441
	v_readlane_b32 s0, v253, 29
	s_nop 1
	v_add_u32_e32 v0, s0, v1

; __device__ __forceinline__ void gemm_tile256(const Params& p, int l, int mt_, int nt_, unsigned char* smem) {
;     ...
; #pragma unroll
;   for (int i = 0; i < 4; ++i) {
;     const int bo = tid * 16 + i * 4096;
;     const int st = bo >> 10, sb = bo & 1023, swz = sb ^ (((sb >> 9) & 1) << 5);
;     sR[i] = st * 16 + (swz >> 6);
;     sC[i] = (swz & 63) >> 1;
;   }
;   const bf16_t* Ag0 = A + (size_t)(m0 + sR[0]) * 1024 + sC[0];
;   const bf16_t* Ag1 = A + (size_t)(m0 + sR[1]) * 1024 + sC[1];
;   const bf16_t* Ag2 = A + (size_t)(m0 + sR[2]) * 1024 + sC[2];
;   const bf16_t* Ag3 = A + (size_t)(m0 + sR[3]) * 1024 + sC[3];
;   const bf16_t* Bg0 = Bt + (size_t)(n0 + sR[0]) * 1024 + sC[0];
;   const bf16_t* Bg1 = Bt + (size_t)(n0 + sR[1]) * 1024 + sC[1];
;     ...
;   const int lo = (fr * 64 + fq * 16) ^ ((fr >> 3) << 5);
;   GQ_STAGE(0, 0);
;   asm volatile("s_waitcnt vmcnt(0)" ::: "memory");
;   __builtin_amdgcn_s_barrier();
; __device__ __forceinline__ void phase_inproj(const Params& p, int l, unsigned char* smem) {
;     ...
;     for (int t = blockIdx.x; t < 64 * 24; t += gridDim.x) { const int ne = t % 24; gemm_tile256(p, l, t / 24, (ne < 16) ? ne : ne + 5, smem); }
.LBB0_947:
	s_mul_hi_i32 s42, s28, 0x2aaaaaab
	s_lshr_b32 s43, s42, 31
	s_ashr_i32 s42, s42, 2
	s_add_i32 s42, s42, s43
	s_mul_i32 s43, s42, 24
	v_mov_b32_e32 v186, v189
	s_sub_i32 s43, s28, s43
	s_add_i32 s44, s43, 5
	v_lshlrev_b32_e32 v14, 4, v186
	v_lshrrev_b32_e32 v216, 2, v186
	v_ashrrev_i32_e32 v1, 2, v186
	v_and_b32_e32 v18, -16, v1
	v_bfi_b32 v10, 15, v216, v1
	v_add_u32_e32 v1, 0x1000, v14
	s_cmp_lt_i32 s43, 16
	v_ashrrev_i32_e32 v1, 6, v1
	s_cselect_b32 s46, s43, s44
	s_lshl_b32 s44, s42, 8
	v_and_b32_e32 v19, -16, v1
	v_bfi_b32 v12, -16, v1, v216
	v_add_u32_e32 v1, 0x2000, v14
	v_ashrrev_i32_e32 v1, 6, v1
	v_add_u32_e32 v2, s44, v10
	v_and_b32_e32 v20, -16, v1
	v_add_u32_e32 v1, 0x3000, v14
	v_ashrrev_i32_e32 v3, 31, v2
	v_readlane_b32 s0, v251, 48
	v_and_b32_e32 v15, 32, v186
	v_bfe_u32 v16, v186, 2, 4
	v_ashrrev_i32_e32 v1, 6, v1
	v_lshlrev_b64 v[2:3], 11, v[2:3]
	v_readlane_b32 s6, v251, 54
	v_readlane_b32 s7, v251, 55
	v_add_u32_e32 v141, 0, v14
	v_bitop3_b32 v0, v14, v15, 48 bitop3:0x6c
	v_and_b32_e32 v21, -16, v1
	v_lshl_add_u64 v[2:3], s[6:7], 0, v[2:3]
	v_mov_b32_e32 v1, v164
	v_add_u32_e32 v4, s44, v12
	v_or_b32_e32 v8, s44, v16
	v_readfirstlane_b32 s42, v141
	v_lshl_add_u64 v[2:3], v[2:3], 0, v[0:1]
	v_ashrrev_i32_e32 v5, 31, v4
	v_add_u32_e32 v6, v8, v20
	s_mov_b32 m0, s42
	s_lshl_b32 s92, s46, 7
	v_lshlrev_b64 v[4:5], 11, v[4:5]
	v_ashrrev_i32_e32 v7, 31, v6
	v_add_u32_e32 v8, v8, v21
	global_load_lds_dwordx4 v[2:3], off
	v_add_u32_e32 v2, 0x1000, v141
	v_lshl_add_u64 v[4:5], s[6:7], 0, v[4:5]
	v_lshlrev_b64 v[6:7], 11, v[6:7]
	v_ashrrev_i32_e32 v9, 31, v8
	v_add_u32_e32 v10, s92, v10
	v_readfirstlane_b32 s42, v2
	v_add_u32_e32 v2, 0x2000, v141
	v_readlane_b32 s1, v251, 49
	v_lshl_add_u64 v[4:5], v[4:5], 0, v[0:1]
	v_lshl_add_u64 v[6:7], s[6:7], 0, v[6:7]
	v_lshlrev_b64 v[8:9], 11, v[8:9]
	v_ashrrev_i32_e32 v11, 31, v10
	v_add_u32_e32 v12, s92, v12
	s_mov_b32 m0, s42
	v_readfirstlane_b32 s42, v2
	v_add_u32_e32 v2, 0x3000, v141
	v_lshl_add_u64 v[6:7], v[6:7], 0, v[0:1]
	v_lshl_add_u64 v[8:9], s[6:7], 0, v[8:9]
	v_lshlrev_b64 v[10:11], 11, v[10:11]
	s_mov_b64 s[0:1], s[82:83]
	v_ashrrev_i32_e32 v13, 31, v12
	global_load_lds_dwordx4 v[4:5], off
	s_mov_b32 m0, s42
	v_readfirstlane_b32 s42, v2
	v_add_u32_e32 v2, 0x4000, v141
	v_lshl_add_u64 v[8:9], v[8:9], 0, v[0:1]
	v_lshl_add_u64 v[10:11], s[0:1], 0, v[10:11]
	v_lshlrev_b64 v[12:13], 11, v[12:13]
	global_load_lds_dwordx4 v[6:7], off
	s_mov_b32 m0, s42
	v_readfirstlane_b32 s42, v2
	v_add_u32_e32 v2, 0x5000, v141
	v_lshl_add_u64 v[10:11], v[10:11], 0, v[0:1]
	v_lshl_add_u64 v[12:13], s[0:1], 0, v[12:13]
	global_load_lds_dwordx4 v[8:9], off
	s_mov_b32 m0, s42
	v_readfirstlane_b32 s42, v2
	v_lshl_add_u64 v[0:1], v[12:13], 0, v[0:1]
	global_load_lds_dwordx4 v[10:11], off
	s_mov_b32 m0, s42
	v_and_b32_e32 v17, 48, v14
	global_load_lds_dwordx4 v[0:1], off
	v_add_u32_e32 v0, s44, v18
	v_or_b32_e32 v0, v0, v16
	v_ashrrev_i32_e32 v1, 31, v0
	v_lshlrev_b64 v[0:1], 11, v[0:1]
	v_readlane_b32 s0, v254, 56
	v_bitop3_b32 v0, v0, v17, v15 bitop3:0xf6
	v_readlane_b32 s1, v254, 57
	v_and_b32_e32 v165, 15, v186
	v_lshlrev_b32_e32 v22, 2, v186
	v_lshl_add_u64 v[92:93], s[0:1], 0, v[0:1]
	v_add_u32_e32 v0, s44, v19
	v_or_b32_e32 v0, v0, v16
	v_ashrrev_i32_e32 v1, 31, v0
	v_lshlrev_b64 v[0:1], 11, v[0:1]
	v_bitop3_b32 v0, v0, v17, v15 bitop3:0xf6
	v_lshl_add_u64 v[94:95], s[0:1], 0, v[0:1]
	v_add_u32_e32 v0, s44, v20
	v_or_b32_e32 v0, v0, v16
	v_ashrrev_i32_e32 v1, 31, v0
	v_lshlrev_b64 v[0:1], 11, v[0:1]
	v_bitop3_b32 v0, v0, v17, v15 bitop3:0xf6
	v_lshl_add_u64 v[132:133], s[0:1], 0, v[0:1]
	v_add_u32_e32 v0, s44, v21
	v_or_b32_e32 v0, v0, v16
	v_ashrrev_i32_e32 v1, 31, v0
	v_lshlrev_b64 v[0:1], 11, v[0:1]
	v_bitop3_b32 v0, v0, v17, v15 bitop3:0xf6
	v_lshl_add_u64 v[134:135], s[0:1], 0, v[0:1]
	v_add_u32_e32 v0, s92, v18
	v_or_b32_e32 v0, v0, v16
	v_ashrrev_i32_e32 v1, 31, v0
	v_lshlrev_b64 v[0:1], 11, v[0:1]
	v_bitop3_b32 v0, v0, v17, v15 bitop3:0xf6
	v_lshl_add_u64 v[136:137], s[94:95], 0, v[0:1]
	v_add_u32_e32 v0, s92, v19
	v_or_b32_e32 v0, v0, v16
	v_ashrrev_i32_e32 v1, 31, v0
	v_lshlrev_b64 v[0:1], 11, v[0:1]
	s_waitcnt vmcnt(0)
	v_bitop3_b32 v0, v0, v17, v15 bitop3:0xf6
	v_lshlrev_b32_e32 v12, 6, v165
	v_and_b32_e32 v13, 48, v186
	v_and_b32_e32 v22, 32, v22
	v_lshl_add_u64 v[138:139], s[94:95], 0, v[0:1]
	v_mov_b32_e32 v0, 0
	v_ashrrev_i32_e32 v217, 6, v186
	v_bitop3_b32 v140, v12, v22, v13 bitop3:0x36
	s_mov_b32 s45, 0
	s_mov_b64 s[42:43], 0
	v_mov_b32_e32 v1, v0
	v_mov_b32_e32 v2, v0
	v_mov_b32_e32 v3, v0
	v_mov_b32_e32 v4, v0
	v_mov_b32_e32 v5, v0
	v_mov_b32_e32 v6, v0
	v_mov_b32_e32 v7, v0
	v_mov_b32_e32 v8, v0
	v_mov_b32_e32 v9, v0
	v_mov_b32_e32 v10, v0
	v_mov_b32_e32 v11, v0
	v_mov_b32_e32 v12, v0
	v_mov_b32_e32 v13, v0
	v_mov_b32_e32 v14, v0
	v_mov_b32_e32 v15, v0
	v_mov_b32_e32 v20, v0
	v_mov_b32_e32 v21, v0
	v_mov_b32_e32 v22, v0
	v_mov_b32_e32 v23, v0
	s_waitcnt vmcnt(0)
; #define MFMA(a, b, c) __builtin_amdgcn_mfma_f32_16x16x32_bf16(a, b, c, 0, 0, 0)
; __device__ __forceinline__ void gemm_tile256(const Params& p, int l, int mt_, int nt_, unsigned char* smem) {
;     ...
;   for (int kt = 0; kt < 32; ++kt) {
;     const int q = kt & 1;
;     if (kt + 1 < 32) GQ_STAGE(q ^ 1, kt + 1);
;     {
;       const unsigned char* Ab = lds + q * 24576 + (w * 4) * 1024 + lo;
;       const unsigned char* Bb = lds + q * 24576 + 16384 + lo;
;       bf16x8 a[4];
; #pragma unroll
;       for (int i = 0; i < 4; ++i) a[i] = *(const bf16x8*)(Ab + i * 1024);
; #pragma unroll
;       for (int jh = 0; jh < 2; ++jh) {
;         bf16x8 b[4];
; #pragma unroll
;         for (int j = 0; j < 4; ++j) b[j] = *(const bf16x8*)(Bb + (jh * 4 + j) * 1024);
; #pragma unroll
;         for (int i = 0; i < 4; ++i)
; #pragma unroll
;           for (int j = 0; j < 4; ++j) acc[i][jh * 4 + j] = MFMA(a[i], b[j], acc[i][jh * 4 + j]);
;       }
;     }
;     asm volatile("s_waitcnt vmcnt(0) lgkmcnt(0)" ::: "memory");
;     __builtin_amdgcn_s_barrier();
;   }
	v_mov_b32_e32 v28, v0
	v_mov_b32_e32 v29, v0
	v_mov_b32_e32 v30, v0
	v_mov_b32_e32 v31, v0
	v_mov_b32_e32 v36, v0
	v_mov_b32_e32 v37, v0
	v_mov_b32_e32 v38, v0
	v_mov_b32_e32 v39, v0
	v_mov_b32_e32 v44, v0
	v_mov_b32_e32 v45, v0
	v_mov_b32_e32 v46, v0
	v_mov_b32_e32 v47, v0
	v_mov_b32_e32 v16, v0
	v_mov_b32_e32 v17, v0
	v_mov_b32_e32 v18, v0
	v_mov_b32_e32 v19, v0
	v_mov_b32_e32 v24, v0
	v_mov_b32_e32 v25, v0
	v_mov_b32_e32 v26, v0
	v_mov_b32_e32 v27, v0
	v_mov_b32_e32 v32, v0
	v_mov_b32_e32 v33, v0
	v_mov_b32_e32 v34, v0
	v_mov_b32_e32 v35, v0
	v_mov_b32_e32 v40, v0
	v_mov_b32_e32 v41, v0
	v_mov_b32_e32 v42, v0
	v_mov_b32_e32 v43, v0
	v_mov_b32_e32 v56, v0
	v_mov_b32_e32 v57, v0
	v_mov_b32_e32 v58, v0
	v_mov_b32_e32 v59, v0
	v_mov_b32_e32 v60, v0
	v_mov_b32_e32 v61, v0
	v_mov_b32_e32 v62, v0
	v_mov_b32_e32 v63, v0
	v_mov_b32_e32 v64, v0
	v_mov_b32_e32 v65, v0
	v_mov_b32_e32 v66, v0
	v_mov_b32_e32 v67, v0
	v_mov_b32_e32 v68, v0
	v_mov_b32_e32 v69, v0
	v_mov_b32_e32 v70, v0
	v_mov_b32_e32 v71, v0
	v_mov_b32_e32 v52, v0
	v_mov_b32_e32 v53, v0
	v_mov_b32_e32 v54, v0
	v_mov_b32_e32 v55, v0
	v_mov_b32_e32 v48, v0
	v_mov_b32_e32 v49, v0
	v_mov_b32_e32 v50, v0
	v_mov_b32_e32 v51, v0
	v_mov_b32_e32 v96, v0
	v_mov_b32_e32 v97, v0
	v_mov_b32_e32 v98, v0
	v_mov_b32_e32 v99, v0
	v_mov_b32_e32 v100, v0
	v_mov_b32_e32 v101, v0
	v_mov_b32_e32 v102, v0
	v_mov_b32_e32 v103, v0
	v_mov_b32_e32 v72, v0
	v_mov_b32_e32 v73, v0
	v_mov_b32_e32 v74, v0
	v_mov_b32_e32 v75, v0
	v_mov_b32_e32 v80, v0
	v_mov_b32_e32 v81, v0
	v_mov_b32_e32 v82, v0
	v_mov_b32_e32 v83, v0
	v_mov_b32_e32 v84, v0
	v_mov_b32_e32 v85, v0
	v_mov_b32_e32 v86, v0
	v_mov_b32_e32 v87, v0
	v_mov_b32_e32 v88, v0
	v_mov_b32_e32 v89, v0
	v_mov_b32_e32 v90, v0
	v_mov_b32_e32 v91, v0
	v_mov_b32_e32 v76, v0
	v_mov_b32_e32 v77, v0
	v_mov_b32_e32 v78, v0
	v_mov_b32_e32 v79, v0
	v_mov_b32_e32 v120, v0
	v_mov_b32_e32 v121, v0
	v_mov_b32_e32 v122, v0
	v_mov_b32_e32 v123, v0
	v_mov_b32_e32 v124, v0
	v_mov_b32_e32 v125, v0
	v_mov_b32_e32 v126, v0
	v_mov_b32_e32 v127, v0
	v_mov_b32_e32 v128, v0
	v_mov_b32_e32 v129, v0
	v_mov_b32_e32 v130, v0
	v_mov_b32_e32 v131, v0
	v_mov_b32_e32 v104, v0
	v_mov_b32_e32 v105, v0
	v_mov_b32_e32 v106, v0
	v_mov_b32_e32 v107, v0
	v_mov_b32_e32 v108, v0
	v_mov_b32_e32 v109, v0
	v_mov_b32_e32 v110, v0
	v_mov_b32_e32 v111, v0
	v_mov_b32_e32 v116, v0
	v_mov_b32_e32 v117, v0
	v_mov_b32_e32 v118, v0
	v_mov_b32_e32 v119, v0
	v_mov_b32_e32 v112, v0
	v_mov_b32_e32 v113, v0
	v_mov_b32_e32 v114, v0
	v_mov_b32_e32 v115, v0
	v_lshlrev_b32_e32 v142, 12, v217
	v_readlane_b32 s2, v251, 50
	v_readlane_b32 s3, v251, 51
	v_readlane_b32 s4, v251, 52
	v_readlane_b32 s5, v251, 53
	v_readlane_b32 s8, v251, 56
	v_readlane_b32 s9, v251, 57
	v_readlane_b32 s10, v251, 58
	v_readlane_b32 s11, v251, 59
	v_readlane_b32 s12, v251, 60
	v_readlane_b32 s13, v251, 61
	v_readlane_b32 s14, v251, 62
	v_readlane_b32 s15, v251, 63
	s_barrier
.LBB0_948:
	s_and_b32 s47, s45, 1
	s_xor_b32 s48, s47, 1
	s_mulk_i32 s48, 0x6000
	v_add_u32_e32 v143, s48, v141
	v_add_u32_e32 v146, 0x1000, v143
	v_readfirstlane_b32 s48, v143
	v_lshl_add_u64 v[144:145], v[92:93], 0, s[42:43]
	s_mov_b32 m0, s48
	v_readfirstlane_b32 s48, v146
	v_add_u32_e32 v146, 0x2000, v143
	global_load_lds_dwordx4 v[144:145], off
	v_lshl_add_u64 v[144:145], v[94:95], 0, s[42:43]
	s_mov_b32 m0, s48
	v_readfirstlane_b32 s48, v146
	v_add_u32_e32 v146, 0x3000, v143
	global_load_lds_dwordx4 v[144:145], off
	v_lshl_add_u64 v[144:145], v[132:133], 0, s[42:43]
	s_mov_b32 m0, s48
	v_readfirstlane_b32 s48, v146
	v_add_u32_e32 v146, 0x4000, v143
	global_load_lds_dwordx4 v[144:145], off
	v_lshl_add_u64 v[144:145], v[134:135], 0, s[42:43]
	s_mov_b32 m0, s48
	v_readfirstlane_b32 s48, v146
	v_add_u32_e32 v143, 0x5000, v143
	global_load_lds_dwordx4 v[144:145], off
	v_lshl_add_u64 v[144:145], v[136:137], 0, s[42:43]
	s_mov_b32 m0, s48
	v_readfirstlane_b32 s48, v143
	global_load_lds_dwordx4 v[144:145], off
	v_lshl_add_u64 v[144:145], v[138:139], 0, s[42:43]
	s_mov_b32 m0, s48
	s_mulk_i32 s47, 0x6000
	global_load_lds_dwordx4 v[144:145], off
	s_add_i32 s47, s47, 0
	v_add_u32_e32 v143, s47, v140
	v_add_u32_e32 v156, v143, v142
	ds_read_b128 v[144:147], v156
	ds_read_b128 v[148:151], v156 offset:1024
	ds_read_b128 v[152:155], v156 offset:2048
	ds_read_b128 v[156:159], v156 offset:3072
	ds_read_b128 v[160:163], v143 offset:16384
	ds_read_b128 v[218:221], v143 offset:17408
	ds_read_b128 v[222:225], v143 offset:18432
	ds_read_b128 v[226:229], v143 offset:19456
	s_waitcnt lgkmcnt(0)
	v_mfma_f32_16x16x32_bf16 v[88:91], v[144:147], v[160:163], v[88:91]
	s_add_i32 s45, s45, 1
	s_add_u32 s42, s42, 64
	s_addc_u32 s43, s43, 0
	v_mfma_f32_16x16x32_bf16 v[84:87], v[144:147], v[218:221], v[84:87]
	s_cmpk_eq_i32 s42, 0x7c0
	v_mfma_f32_16x16x32_bf16 v[80:83], v[144:147], v[222:225], v[80:83]
	v_mfma_f32_16x16x32_bf16 v[72:75], v[144:147], v[226:229], v[72:75]
	v_mfma_f32_16x16x32_bf16 v[68:71], v[148:151], v[160:163], v[68:71]
	v_mfma_f32_16x16x32_bf16 v[64:67], v[148:151], v[218:221], v[64:67]
	v_mfma_f32_16x16x32_bf16 v[60:63], v[148:151], v[222:225], v[60:63]
	v_mfma_f32_16x16x32_bf16 v[56:59], v[148:151], v[226:229], v[56:59]
	v_mfma_f32_16x16x32_bf16 v[44:47], v[152:155], v[160:163], v[44:47]
	v_mfma_f32_16x16x32_bf16 v[36:39], v[152:155], v[218:221], v[36:39]
	v_mfma_f32_16x16x32_bf16 v[28:31], v[152:155], v[222:225], v[28:31]
	v_mfma_f32_16x16x32_bf16 v[20:23], v[152:155], v[226:229], v[20:23]
	v_mfma_f32_16x16x32_bf16 v[76:79], v[156:159], v[160:163], v[76:79]
	v_mfma_f32_16x16x32_bf16 v[120:123], v[156:159], v[218:221], v[120:123]
	v_mfma_f32_16x16x32_bf16 v[124:127], v[156:159], v[222:225], v[124:127]
	v_mfma_f32_16x16x32_bf16 v[128:131], v[156:159], v[226:229], v[128:131]
	ds_read_b128 v[160:163], v143 offset:20480
	ds_read_b128 v[218:221], v143 offset:21504
	ds_read_b128 v[222:225], v143 offset:22528
	ds_read_b128 v[226:229], v143 offset:23552
	s_waitcnt vmcnt(0) lgkmcnt(0)
	s_barrier
; #define MFMA(a, b, c) __builtin_amdgcn_mfma_f32_16x16x32_bf16(a, b, c, 0, 0, 0)
; __device__ __forceinline__ void gemm_tile256(const Params& p, int l, int mt_, int nt_, unsigned char* smem) {
;     ...
;     {
;       const unsigned char* Ab = lds + q * 24576 + (w * 4) * 1024 + lo;
;       const unsigned char* Bb = lds + q * 24576 + 16384 + lo;
;       bf16x8 a[4];
; #pragma unroll
;       for (int i = 0; i < 4; ++i) a[i] = *(const bf16x8*)(Ab + i * 1024);
; #pragma unroll
;       for (int jh = 0; jh < 2; ++jh) {
;         bf16x8 b[4];
; #pragma unroll
;         for (int j = 0; j < 4; ++j) b[j] = *(const bf16x8*)(Bb + (jh * 4 + j) * 1024);
; #pragma unroll
;         for (int i = 0; i < 4; ++i)
; #pragma unroll
;           for (int j = 0; j < 4; ++j) acc[i][jh * 4 + j] = MFMA(a[i], b[j], acc[i][jh * 4 + j]);
;       }
;     }
;     asm volatile("s_waitcnt vmcnt(0) lgkmcnt(0)" ::: "memory");
;     __builtin_amdgcn_s_barrier();
;   }
; #pragma unroll
;   for (int hc = 0; hc < 2; ++hc) {
;     const int cbase = n0 + hc * 64;
;     bf16_t* dst;
;     int ld, coff;
;     if (cbase < 1024) { dst = p.PA; ld = 1024; coff = cbase; }
;     else if (cbase < 2048) { dst = p.PR; ld = 1024; coff = cbase - 1024; }
;     else if (cbase < 2688) { dst = p.PG; ld = 640; coff = cbase - 2048; }
;     else { dst = p.PS; ld = 912; coff = cbase - 2688; }
	s_waitcnt lgkmcnt(0)
	v_mfma_f32_16x16x32_bf16 v[100:103], v[144:147], v[160:163], v[100:103]
	v_mfma_f32_16x16x32_bf16 v[96:99], v[144:147], v[218:221], v[96:99]
	v_mfma_f32_16x16x32_bf16 v[48:51], v[144:147], v[222:225], v[48:51]
	v_mfma_f32_16x16x32_bf16 v[52:55], v[144:147], v[226:229], v[52:55]
	v_mfma_f32_16x16x32_bf16 v[40:43], v[148:151], v[160:163], v[40:43]
	v_mfma_f32_16x16x32_bf16 v[32:35], v[148:151], v[218:221], v[32:35]
	v_mfma_f32_16x16x32_bf16 v[24:27], v[148:151], v[222:225], v[24:27]
	v_mfma_f32_16x16x32_bf16 v[16:19], v[148:151], v[226:229], v[16:19]
	v_mfma_f32_16x16x32_bf16 v[12:15], v[152:155], v[160:163], v[12:15]
	v_mfma_f32_16x16x32_bf16 v[8:11], v[152:155], v[218:221], v[8:11]
	v_mfma_f32_16x16x32_bf16 v[4:7], v[152:155], v[222:225], v[4:7]
	v_mfma_f32_16x16x32_bf16 v[0:3], v[152:155], v[226:229], v[0:3]
	v_mfma_f32_16x16x32_bf16 v[104:107], v[156:159], v[160:163], v[104:107]
	v_mfma_f32_16x16x32_bf16 v[108:111], v[156:159], v[218:221], v[108:111]
	v_mfma_f32_16x16x32_bf16 v[116:119], v[156:159], v[222:225], v[116:119]
	v_mfma_f32_16x16x32_bf16 v[112:115], v[156:159], v[226:229], v[112:115]
	s_cbranch_scc0 .LBB0_948
	v_add_u32_e32 v182, 0, v142
	v_add_u32_e32 v92, v182, v140
	ds_read_b128 v[218:221], v92 offset:24576
	v_add_u32_e32 v250, 0, v140
	ds_read_b128 v[222:225], v250 offset:40960
	ds_read_b128 v[226:229], v250 offset:41984
	ds_read_b128 v[230:233], v92 offset:25600
	ds_read_b128 v[234:237], v250 offset:43008
	ds_read_b128 v[238:241], v250 offset:44032
	ds_read_b128 v[242:245], v92 offset:26624
	ds_read_b128 v[246:249], v92 offset:27648
	s_waitcnt lgkmcnt(0)
	v_mfma_f32_16x16x32_bf16 v[144:147], v[230:233], v[226:229], v[64:67]
	s_cmp_gt_i32 s46, 7
	v_mfma_f32_16x16x32_bf16 v[152:155], v[218:221], v[238:241], v[72:75]
	v_mfma_f32_16x16x32_bf16 v[72:75], v[246:249], v[222:225], v[76:79]
	v_mfma_f32_16x16x32_bf16 v[76:79], v[246:249], v[226:229], v[120:123]
	v_mfma_f32_16x16x32_bf16 v[64:67], v[246:249], v[234:237], v[124:127]
	s_nop 1
	ds_read_b128 v[120:123], v250 offset:45056
	ds_read_b128 v[124:127], v250 offset:46080
	v_mfma_f32_16x16x32_bf16 v[132:135], v[230:233], v[234:237], v[60:63]
	v_mfma_f32_16x16x32_bf16 v[136:139], v[230:233], v[238:241], v[56:59]
	s_waitcnt lgkmcnt(0)
	v_mfma_f32_16x16x32_bf16 v[56:59], v[218:221], v[120:123], v[100:103]
	v_mfma_f32_16x16x32_bf16 v[60:63], v[218:221], v[124:127], v[96:99]
	s_nop 2
	ds_read_b128 v[96:99], v250 offset:47104
	ds_read_b128 v[100:103], v250 offset:48128
	s_waitcnt vmcnt(0) lgkmcnt(0)
	s_barrier
	v_mfma_f32_16x16x32_bf16 v[156:159], v[218:221], v[222:225], v[88:91]
	v_mfma_f32_16x16x32_bf16 v[160:163], v[218:221], v[226:229], v[84:87]
	v_mfma_f32_16x16x32_bf16 v[148:151], v[218:221], v[234:237], v[80:83]
	v_mfma_f32_16x16x32_bf16 v[140:143], v[230:233], v[222:225], v[68:71]
	v_mfma_f32_16x16x32_bf16 v[88:91], v[242:245], v[222:225], v[44:47]
	v_mfma_f32_16x16x32_bf16 v[92:95], v[242:245], v[226:229], v[36:39]
	v_mfma_f32_16x16x32_bf16 v[80:83], v[242:245], v[234:237], v[28:31]
	v_mfma_f32_16x16x32_bf16 v[84:87], v[242:245], v[238:241], v[20:23]
	v_mfma_f32_16x16x32_bf16 v[68:71], v[246:249], v[238:241], v[128:131]
	s_waitcnt lgkmcnt(0)
	v_mfma_f32_16x16x32_bf16 v[48:51], v[218:221], v[96:99], v[48:51]
	v_mfma_f32_16x16x32_bf16 v[52:55], v[218:221], v[100:103], v[52:55]
	v_mfma_f32_16x16x32_bf16 v[40:43], v[230:233], v[120:123], v[40:43]
	v_mfma_f32_16x16x32_bf16 v[44:47], v[230:233], v[124:127], v[32:35]
	v_mfma_f32_16x16x32_bf16 v[32:35], v[230:233], v[96:99], v[24:27]
	v_mfma_f32_16x16x32_bf16 v[36:39], v[230:233], v[100:103], v[16:19]
	v_mfma_f32_16x16x32_bf16 v[24:27], v[242:245], v[120:123], v[12:15]
	v_mfma_f32_16x16x32_bf16 v[28:31], v[242:245], v[124:127], v[8:11]
	v_mfma_f32_16x16x32_bf16 v[16:19], v[242:245], v[96:99], v[4:7]
	v_mfma_f32_16x16x32_bf16 v[20:23], v[242:245], v[100:103], v[0:3]
	v_mfma_f32_16x16x32_bf16 v[8:11], v[246:249], v[120:123], v[104:107]
	v_mfma_f32_16x16x32_bf16 v[12:15], v[246:249], v[124:127], v[108:111]
	v_mfma_f32_16x16x32_bf16 v[0:3], v[246:249], v[96:99], v[116:119]
	v_mfma_f32_16x16x32_bf16 v[4:7], v[246:249], v[100:103], v[112:115]
	s_cbranch_scc0 .LBB0_953
	s_cmpk_gt_u32 s92, 0x7ff
	s_cbranch_scc0 .LBB0_954
	s_cmpk_gt_u32 s92, 0xa7f
	s_cbranch_scc0 .LBB0_955
	v_readlane_b32 s0, v251, 48
	v_readlane_b32 s14, v251, 62
	v_readlane_b32 s15, v251, 63
	s_add_i32 s96, s92, 0xfffff580
	v_readlane_b32 s1, v251, 49
	v_readlane_b32 s2, v251, 50
	v_readlane_b32 s3, v251, 51
	v_readlane_b32 s4, v251, 52
	v_readlane_b32 s5, v251, 53
	v_readlane_b32 s6, v251, 54
	v_readlane_b32 s7, v251, 55
	v_readlane_b32 s8, v251, 56
	v_readlane_b32 s9, v251, 57
	v_readlane_b32 s10, v251, 58
	v_readlane_b32 s11, v251, 59
	v_readlane_b32 s12, v251, 60
	v_readlane_b32 s13, v251, 61
	s_mov_b64 s[76:77], s[14:15]
	s_mov_b64 s[78:79], 0x390
	s_cbranch_execz .LBB0_956
	s_branch .LBB0_957

; template <bool DUAL>
; __device__ __forceinline__ void rwkv_tile(const Params& p, int l, int tile, unsigned char* smem) {
;     ...
;   const int lc = (tid & 15) * 4;
;   const float* mu0 = p.rwkv_mu + (size_t)(l * 2 + 0) * 1024 + h * 64 + lc;
;   const float* mu1 = p.rwkv_mu + (size_t)(l * 2 + 1) * 1024 + h * 64 + lc;
;   const float4 m0r = *(const float4*)mu0, m1r = *(const float4*)mu1;
;   const float4 m0k = *(const float4*)(mu0 + 256), m1k = *(const float4*)(mu1 + 256);
;   const float4 m0v = *(const float4*)(mu0 + 512), m1v = *(const float4*)(mu1 + 512);
;   const float4 ka4 = *(const float4*)(p.rwkv_k_a + ld2 * 256 + h * 64 + lc);
;   v2f sA = {0.f, 0.f}, sB = {0.f, 0.f};
;   v2f iA = {(row == c0) ? 1.f : 0.f, (row == c0 + 1) ? 1.f : 0.f}, iB = {(row == c0 + 2) ? 1.f : 0.f, (row == c0 + 3) ? 1.f : 0.f};
;   const int pcc = tid % 24, prow = tid / 24;
;   const bool pact = tid < 240;
;   const bf16_t* rbase_g = p.PR + rowbase * 1024 + (pcc >> 3) * 256 + h * 64 + (pcc & 7) * 8;
;   const bf16_t* pbase_g = p.PRE + (size_t)(pcc >> 3) * PRE_ARR + (rowbase * 2 + d) * 256 + h * 64 + (pcc & 7) * 8;
;   uint4 pf0, pf1, pf2, pf3, pg0, pg1, pg2, pg3;
.LBB0_1385:
	s_setprio 2
	v_readlane_b32 s0, v255, 40
	s_lshl_b32 s42, s0, 1
	v_readlane_b32 s0, v254, 18
	s_ashr_i32 s43, s42, 31
	v_readlane_b32 s1, v255, 41
	s_or_b32 s28, s42, s0
	s_lshl_b64 s[44:45], s[42:43], 12
	v_readlane_b32 s0, v254, 0
	s_add_u32 s44, s0, s44
	v_readlane_b32 s1, v254, 1
	s_addc_u32 s45, s1, s45
	s_or_b32 s42, s42, 1
	s_ashr_i32 s43, s42, 31
	s_lshl_b64 s[42:43], s[42:43], 12
	s_add_u32 s42, s0, s42
	v_mov_b32_e32 v61, v189
	s_addc_u32 s43, s1, s43
	s_lshl_b32 s46, s28, 8
	s_ashr_i32 s47, s46, 31
	v_lshlrev_b32_e32 v0, 2, v61
	v_and_b32_e32 v60, 60, v0
	s_lshl_b64 s[46:47], s[46:47], 2
	v_readlane_b32 s0, v254, 6
	v_lshlrev_b32_e32 v24, 2, v60
	s_add_u32 s46, s0, s46
	v_readlane_b32 s0, v254, 7
	global_load_dwordx4 v[0:3], v24, s[42:43]
	global_load_dwordx4 v[4:7], v24, s[44:45] offset:2048
	s_addc_u32 s47, s0, s47
	global_load_dwordx4 v[8:11], v24, s[44:45]
	global_load_dwordx4 v[12:15], v24, s[44:45] offset:1024
	global_load_dwordx4 v[16:19], v24, s[42:43] offset:2048
	global_load_dwordx4 v[20:23], v24, s[42:43] offset:1024
	s_nop 0
	global_load_dwordx4 v[24:27], v24, s[46:47]
	s_mov_b32 s0, 0x2aaaaaab
	s_waitcnt vmcnt(7)
	v_mul_hi_i32 v28, v61, s0
	v_lshrrev_b32_e32 v29, 31, v28
	v_ashrrev_i32_e32 v28, 2, v28
	v_add_u32_e32 v97, v28, v29
	v_mul_lo_u32 v28, v97, 24
	v_sub_u32_e32 v30, v61, v28
	s_movk_i32 s0, 0xef
	v_cmp_lt_i32_e32 vcc, s0, v61
	s_movk_i32 s0, 0xf0
	v_ashrrev_i32_e32 v46, 3, v30
	v_cmp_gt_i32_e64 s[42:43], s0, v61
	v_lshlrev_b32_e32 v28, 8, v46
	v_readlane_b32 s0, v254, 8
	v_ashrrev_i32_e32 v29, 31, v28
	v_readlane_b32 s1, v254, 9
	v_lshlrev_b32_e32 v62, 3, v30
	v_and_b32_e32 v30, 56, v62
	v_lshl_add_u64 v[28:29], v[28:29], 1, s[0:1]
	v_readlane_b32 s0, v254, 20
	v_lshlrev_b32_e32 v44, 1, v30
	v_mov_b32_e32 v45, v164
	v_add_u32_e32 v30, s0, v97
	v_lshl_add_u64 v[80:81], v[28:29], 0, v[44:45]
	v_add_u32_e32 v28, 0xffffff00, v30
	v_cmp_gt_u32_e64 s[44:45], s31, v28
	v_mov_b32_e32 v28, v164
	v_mov_b32_e32 v29, v164
	s_and_b64 s[46:47], s[42:43], s[44:45]
	v_mov_b64_e32 v[32:33], v[28:29]
	v_mov_b64_e32 v[34:35], v[28:29]
	s_and_saveexec_b64 s[44:45], s[46:47]
	s_cbranch_execz .LBB0_1387
	v_lshlrev_b32_e32 v30, 11, v30
	v_mov_b32_e32 v31, v164
	v_lshl_add_u64 v[30:31], v[80:81], 0, v[30:31]
	global_load_dwordx4 v[32:35], v[30:31], off

; __device__ __forceinline__ bf16_t f2bf(float f) { return (bf16_t)(pack2(f, 0.f) & 0xffffu); }
; template <bool DUAL>
; __device__ __forceinline__ void rwkv_tile(const Params& p, int l, int tile, unsigned char* smem) {
;     ...
;   for (int cix = cbeg; cix < cend; ++cix) {
;     int plo, slo, shi;
;     RW_GEOM(cix, plo, slo, shi);
;     ...
;         if ((i & 15) == 15) {
;           const int ii = (i & 16) + fr;
;           const int ri = (d == 0) ? ii + 1 : 32 - ii;
;           const int pi = plo - 1 + ri;
;           p.yR[((size_t)d * TOK + rowbase + pi) * 256 + h * 64 + row] = f2bf(ykeep);
;           if (DUAL) p.GID[((size_t)(d * 4 + b) * NSEG1 + (cix - CSPLIT) * 32 + ii) * 256 + h * 64 + row] = f2bf(gkeep);
.LBB0_1429:
	s_lshl_b32 s53, s28, 5
	s_sub_i32 s28, 0x11e0, s53
	s_and_b64 s[50:51], s[36:37], exec
	s_cselect_b32 s28, s53, s28
	s_addk_i32 s53, 0xf640
	s_add_i32 s28, s28, -1
	s_ashr_i32 s50, s53, 31
	v_readlane_b32 s0, v254, 37
	s_add_u32 s53, s53, s0
	s_addc_u32 s54, s50, 0
	s_branch .Lrw_du_scan

; template <bool DUAL>
; __device__ __forceinline__ void rwkv_tile(const Params& p, int l, int tile, unsigned char* smem) {
;     ...
;   const int lc = (tid & 15) * 4;
;   const float* mu0 = p.rwkv_mu + (size_t)(l * 2 + 0) * 1024 + h * 64 + lc;
;   const float* mu1 = p.rwkv_mu + (size_t)(l * 2 + 1) * 1024 + h * 64 + lc;
;   const float4 m0r = *(const float4*)mu0, m1r = *(const float4*)mu1;
;   const float4 m0k = *(const float4*)(mu0 + 256), m1k = *(const float4*)(mu1 + 256);
;   const float4 m0v = *(const float4*)(mu0 + 512), m1v = *(const float4*)(mu1 + 512);
;   const float4 ka4 = *(const float4*)(p.rwkv_k_a + ld2 * 256 + h * 64 + lc);
;   v2f sA = {0.f, 0.f}, sB = {0.f, 0.f};
;   v2f iA = {(row == c0) ? 1.f : 0.f, (row == c0 + 1) ? 1.f : 0.f}, iB = {(row == c0 + 2) ? 1.f : 0.f, (row == c0 + 3) ? 1.f : 0.f};
;   const int pcc = tid % 24, prow = tid / 24;
;   const bool pact = tid < 240;
;   const bf16_t* rbase_g = p.PR + rowbase * 1024 + (pcc >> 3) * 256 + h * 64 + (pcc & 7) * 8;
;   const bf16_t* pbase_g = p.PRE + (size_t)(pcc >> 3) * PRE_ARR + (rowbase * 2 + d) * 256 + h * 64 + (pcc & 7) * 8;
;   uint4 pf0, pf1, pf2, pf3, pg0, pg1, pg2, pg3;
.LBB0_1443:
	s_setprio 2
	v_readlane_b32 s0, v255, 40
	s_lshl_b32 s42, s0, 1
	v_readlane_b32 s0, v254, 18
	s_ashr_i32 s43, s42, 31
	v_readlane_b32 s1, v255, 41
	s_or_b32 s28, s42, s0
	s_lshl_b64 s[44:45], s[42:43], 12
	v_readlane_b32 s0, v254, 25
	s_add_u32 s44, s0, s44
	v_readlane_b32 s1, v254, 26
	s_addc_u32 s45, s1, s45
	s_or_b32 s42, s42, 1
	s_ashr_i32 s43, s42, 31
	s_lshl_b64 s[42:43], s[42:43], 12
	s_add_u32 s42, s0, s42
	v_mov_b32_e32 v61, v189
	s_addc_u32 s43, s1, s43
	s_lshl_b32 s46, s28, 8
	s_ashr_i32 s47, s46, 31
	v_lshlrev_b32_e32 v0, 2, v61
	v_and_b32_e32 v60, 60, v0
	s_lshl_b64 s[46:47], s[46:47], 2
	v_readlane_b32 s0, v254, 27
	v_lshlrev_b32_e32 v24, 2, v60
	s_add_u32 s46, s0, s46
	v_readlane_b32 s0, v254, 28
	global_load_dwordx4 v[0:3], v24, s[42:43]
	global_load_dwordx4 v[4:7], v24, s[44:45] offset:2048
	s_addc_u32 s47, s0, s47
	global_load_dwordx4 v[8:11], v24, s[44:45]
	global_load_dwordx4 v[12:15], v24, s[44:45] offset:1024
	global_load_dwordx4 v[16:19], v24, s[42:43] offset:2048
	global_load_dwordx4 v[20:23], v24, s[42:43] offset:1024
	s_nop 0
	global_load_dwordx4 v[24:27], v24, s[46:47]
	s_mov_b32 s0, 0x2aaaaaab
	s_waitcnt vmcnt(7)
	v_mul_hi_i32 v28, v61, s0
	v_lshrrev_b32_e32 v29, 31, v28
	v_ashrrev_i32_e32 v28, 2, v28
	v_add_u32_e32 v93, v28, v29
	v_mul_lo_u32 v28, v93, 24
	v_sub_u32_e32 v30, v61, v28
	s_movk_i32 s0, 0xef
	v_cmp_lt_i32_e32 vcc, s0, v61
	s_movk_i32 s0, 0xf0
	v_ashrrev_i32_e32 v48, 3, v30
	v_cmp_gt_i32_e64 s[42:43], s0, v61
	v_lshlrev_b32_e32 v28, 8, v48
	v_readlane_b32 s0, v254, 29
	v_ashrrev_i32_e32 v29, 31, v28
	v_readlane_b32 s1, v254, 30
	v_lshlrev_b32_e32 v62, 3, v30
	v_and_b32_e32 v30, 56, v62
	v_lshl_add_u64 v[28:29], v[28:29], 1, s[0:1]
	v_readlane_b32 s0, v254, 34
	v_lshlrev_b32_e32 v44, 1, v30
	v_readlane_b32 s1, v254, 16
	v_add_u32_e32 v30, s0, v93
	v_readlane_b32 s0, v254, 15
	v_mov_b32_e32 v45, v164
	v_cmp_le_i32_e64 s[44:45], s1, v30
	v_cmp_ge_i32_e64 s[46:47], s0, v30
	v_lshl_add_u64 v[84:85], v[28:29], 0, v[44:45]
	s_and_b64 s[44:45], s[44:45], s[46:47]
	v_mov_b32_e32 v28, v164
	v_mov_b32_e32 v29, v164
	s_and_b64 s[46:47], s[42:43], s[44:45]
	v_mov_b64_e32 v[32:33], v[28:29]
	v_mov_b64_e32 v[34:35], v[28:29]
	s_and_saveexec_b64 s[44:45], s[46:47]
	s_cbranch_execz .LBB0_1445
	v_mov_b32_e32 v31, v164
	v_lshlrev_b64 v[30:31], 11, v[30:31]
	v_lshl_add_u64 v[30:31], v[84:85], 0, v[30:31]
	global_load_dwordx4 v[32:35], v[30:31], off

; __device__ __forceinline__ bf16_t f2bf(float f) { return (bf16_t)(pack2(f, 0.f) & 0xffffu); }
; template <bool DUAL>
; __device__ __forceinline__ void rwkv_tile(const Params& p, int l, int tile, unsigned char* smem) {
;     ...
;         if ((i & 15) == 15) {
;           const int ii = (i & 16) + fr;
;           const int ri = (d == 0) ? ii + 1 : 32 - ii;
;           const int pi = plo - 1 + ri;
;           p.yR[((size_t)d * TOK + rowbase + pi) * 256 + h * 64 + row] = f2bf(ykeep);
.LBB0_1486:
	s_lshl_b32 s28, s28, 5
	s_sub_i32 s57, 0xe0, s28
	s_sub_i32 s58, 0x11e0, s28
	s_and_b64 s[50:51], s[36:37], exec
	s_cselect_b32 s50, s28, s58
	s_cselect_b32 s51, s28, s57
	s_cmpk_lt_u32 s28, 0x100
	s_cselect_b32 s28, s51, s50
	s_add_i32 s28, s28, -1
	s_branch .Lrw_nd_scan

; template <bool DUAL>
; __device__ __forceinline__ void rwkv_tile(const Params& p, int l, int tile, unsigned char* smem) {
;     ...
; #pragma unroll 2
;       for (int i = 0; i < 32; ++i) {
;         const int inx = (i + 1) & 31;
;         const float4 nw4 = *(const float4*)(rp + inx * 384), nkk4 = *(const float4*)(rp + inx * 384 + 64), nkb4 = *(const float4*)(rp + inx * 384 + 128);
;         const float4 nkd4 = *(const float4*)(rp + inx * 384 + 192), nr4 = *(const float4*)(rp + inx * 384 + 256);
;         const float nv = vp[inx * 384];
;         v2f t = sA * (v2f){kk4.x, kk4.y};
;         t = sB * (v2f){kk4.z, kk4.w} + t;
;         float sa = t.x + t.y, ia = 0.f;
;         if (DUAL) {
;           v2f ti = iA * (v2f){kk4.x, kk4.y};
;           ti = iB * (v2f){kk4.z, kk4.w} + ti;
;           ia = ti.x + ti.y;
;           sa += dppf<0xB1>(sa); ia += dppf<0xB1>(ia);
;           sa += dppf<0x4E>(sa); ia += dppf<0x4E>(ia);
;           sa += dppf<0x141>(sa); ia += dppf<0x141>(ia);
;           sa += dppf<0x140>(sa); ia += dppf<0x140>(ia);
;         } else {
;           sa = sum16(sa);
;         }
;         v2f cA = sA * (v2f){w4.x, w4.y} + (v2f){kd4.x, kd4.y} * v;
;         v2f cB = sB * (v2f){w4.z, w4.w} + (v2f){kd4.z, kd4.w} * v;
;         sA = cA - (v2f){kb4.x, kb4.y} * sa;
;         sB = cB - (v2f){kb4.z, kb4.w} * sa;
;         v2f u = sA * (v2f){r4.x, r4.y};
;         u = sB * (v2f){r4.z, r4.w} + u;
;         float y = u.x + u.y, g = 0.f;
;         if (DUAL) {
;           iA = iA * (v2f){w4.x, w4.y} - (v2f){kb4.x, kb4.y} * ia;
;           iB = iB * (v2f){w4.z, w4.w} - (v2f){kb4.z, kb4.w} * ia;
;           v2f ui = iA * (v2f){r4.x, r4.y};
;           ui = iB * (v2f){r4.z, r4.w} + ui;
;           g = ui.x + ui.y;
;           y += dppf<0xB1>(y); g += dppf<0xB1>(g);
;           y += dppf<0x4E>(y); g += dppf<0x4E>(g);
;           y += dppf<0x141>(y); g += dppf<0x141>(g);
;           y += dppf<0x140>(y); g += dppf<0x140>(g);
;           if (fr == (i & 15)) gkeep = g;
;         } else {
;           y = sum16(y);
;         }
;         if (fr == (i & 15)) ykeep = y;
.Lrw_du_scan:
	v_mov_b32_e32 v74, v102
	v_mov_b32_e32 v75, v103
	v_add_u32_e32 v68, 1, v101
	v_and_b32_e32 v68, 15, v68
	ds_read_b128 v[220:223], v74 offset:25600
	ds_read_b128 v[216:219], v74 offset:25344
	ds_read_b128 v[228:231], v74 offset:26112
	ds_read_b32 v236, v75 offset:26624
	ds_read_b128 v[224:227], v74 offset:25856
	ds_read_b128 v[232:235], v74 offset:26368
	ds_read_b128 v[126:129], v74 offset:27136
	ds_read_b128 v[122:125], v74 offset:26880
	ds_read_b128 v[134:137], v74 offset:27648
	ds_read_b32 v142, v75 offset:28160
	ds_read_b128 v[130:133], v74 offset:27392
	ds_read_b128 v[138:141], v74 offset:27904
	s_mov_b32 s55, 0
.Lrw_du_loop:
	s_waitcnt lgkmcnt(6)
	v_pk_mul_f32 v[60:61], v[94:95], v[220:221]
	v_pk_mul_f32 v[62:63], v[88:89], v[220:221]
	v_pk_fma_f32 v[60:61], v[92:93], v[222:223], v[60:61]
	v_pk_fma_f32 v[62:63], v[90:91], v[222:223], v[62:63]
	v_add_f32_e32 v64, v64, v65
	v_add_f32_e32 v66, v66, v67
	v_add_f32_e32 v60, v60, v61
	v_add_f32_e32 v62, v62, v63
	v_pk_mul_f32 v[94:95], v[94:95], v[216:217]
	v_pk_mul_f32 v[92:93], v[92:93], v[218:219]
	v_add_f32_dpp v60, v60, v60 quad_perm:[1,0,3,2] row_mask:0xf bank_mask:0xf bound_ctrl:1
	v_add_f32_dpp v62, v62, v62 quad_perm:[1,0,3,2] row_mask:0xf bank_mask:0xf bound_ctrl:1
	v_add_f32_dpp v64, v64, v64 quad_perm:[1,0,3,2] row_mask:0xf bank_mask:0xf bound_ctrl:1
	v_add_f32_dpp v66, v66, v66 quad_perm:[1,0,3,2] row_mask:0xf bank_mask:0xf bound_ctrl:1
	v_pk_fma_f32 v[94:95], v[236:237], v[228:229], v[94:95] op_sel_hi:[0,1,1]
	v_add_f32_dpp v60, v60, v60 quad_perm:[2,3,0,1] row_mask:0xf bank_mask:0xf bound_ctrl:1
	v_add_f32_dpp v62, v62, v62 quad_perm:[2,3,0,1] row_mask:0xf bank_mask:0xf bound_ctrl:1
	v_add_f32_dpp v64, v64, v64 quad_perm:[2,3,0,1] row_mask:0xf bank_mask:0xf bound_ctrl:1
	v_add_f32_dpp v66, v66, v66 quad_perm:[2,3,0,1] row_mask:0xf bank_mask:0xf bound_ctrl:1
	v_pk_fma_f32 v[92:93], v[236:237], v[230:231], v[92:93] op_sel_hi:[0,1,1]
	v_add_f32_dpp v60, v60, v60 row_half_mirror row_mask:0xf bank_mask:0xf bound_ctrl:1
	v_add_f32_dpp v62, v62, v62 row_half_mirror row_mask:0xf bank_mask:0xf bound_ctrl:1
	v_add_f32_dpp v64, v64, v64 row_half_mirror row_mask:0xf bank_mask:0xf bound_ctrl:1
	v_add_f32_dpp v66, v66, v66 row_half_mirror row_mask:0xf bank_mask:0xf bound_ctrl:1
	v_cmp_eq_u32_e32 vcc, 0, v68
	v_add_f32_dpp v60, v60, v60 row_mirror row_mask:0xf bank_mask:0xf bound_ctrl:1
	v_add_f32_dpp v62, v62, v62 row_mirror row_mask:0xf bank_mask:0xf bound_ctrl:1
	v_add_f32_dpp v64, v64, v64 row_mirror row_mask:0xf bank_mask:0xf bound_ctrl:1
	v_add_f32_dpp v66, v66, v66 row_mirror row_mask:0xf bank_mask:0xf bound_ctrl:1
	v_pk_fma_f32 v[94:95], v[224:225], v[60:61], v[94:95] op_sel_hi:[1,0,1] neg_lo:[1,0,0] neg_hi:[1,0,0]
	v_pk_fma_f32 v[92:93], v[226:227], v[60:61], v[92:93] op_sel_hi:[1,0,1] neg_lo:[1,0,0] neg_hi:[1,0,0]
	v_pk_mul_f32 v[238:239], v[224:225], v[62:63] op_sel_hi:[1,0]
	v_pk_mul_f32 v[240:241], v[226:227], v[62:63] op_sel_hi:[1,0]
	v_cndmask_b32_e32 v72, v72, v64, vcc
	v_cndmask_b32_e32 v73, v73, v66, vcc
	v_pk_mul_f32 v[64:65], v[232:233], v[94:95]
	v_pk_fma_f32 v[88:89], v[88:89], v[216:217], v[238:239] neg_lo:[0,0,1] neg_hi:[0,0,1]
	v_pk_fma_f32 v[90:91], v[90:91], v[218:219], v[240:241] neg_lo:[0,0,1] neg_hi:[0,0,1]
	v_pk_fma_f32 v[64:65], v[234:235], v[92:93], v[64:65]
	v_pk_mul_f32 v[66:67], v[232:233], v[88:89]
	v_pk_fma_f32 v[66:67], v[234:235], v[90:91], v[66:67]
	ds_read_b128 v[148:151], v74 offset:28672
	ds_read_b128 v[144:147], v74 offset:28416
	ds_read_b128 v[156:159], v74 offset:29184
	ds_read_b32 v96, v75 offset:29696
	ds_read_b128 v[152:155], v74 offset:28928
	ds_read_b128 v[160:163], v74 offset:29440
	s_waitcnt lgkmcnt(6)
	v_pk_mul_f32 v[60:61], v[94:95], v[126:127]
	v_pk_mul_f32 v[62:63], v[88:89], v[126:127]
	v_pk_fma_f32 v[60:61], v[92:93], v[128:129], v[60:61]
	v_pk_fma_f32 v[62:63], v[90:91], v[128:129], v[62:63]
	v_add_f32_e32 v64, v64, v65
	v_add_f32_e32 v66, v66, v67
	v_add_f32_e32 v60, v60, v61
	v_add_f32_e32 v62, v62, v63
	v_pk_mul_f32 v[94:95], v[94:95], v[122:123]
	v_pk_mul_f32 v[92:93], v[92:93], v[124:125]
	v_add_f32_dpp v60, v60, v60 quad_perm:[1,0,3,2] row_mask:0xf bank_mask:0xf bound_ctrl:1
	v_add_f32_dpp v62, v62, v62 quad_perm:[1,0,3,2] row_mask:0xf bank_mask:0xf bound_ctrl:1
	v_add_f32_dpp v64, v64, v64 quad_perm:[1,0,3,2] row_mask:0xf bank_mask:0xf bound_ctrl:1
	v_add_f32_dpp v66, v66, v66 quad_perm:[1,0,3,2] row_mask:0xf bank_mask:0xf bound_ctrl:1
	v_pk_fma_f32 v[94:95], v[142:143], v[134:135], v[94:95] op_sel_hi:[0,1,1]
	v_add_f32_dpp v60, v60, v60 quad_perm:[2,3,0,1] row_mask:0xf bank_mask:0xf bound_ctrl:1
	v_add_f32_dpp v62, v62, v62 quad_perm:[2,3,0,1] row_mask:0xf bank_mask:0xf bound_ctrl:1
	v_add_f32_dpp v64, v64, v64 quad_perm:[2,3,0,1] row_mask:0xf bank_mask:0xf bound_ctrl:1
	v_add_f32_dpp v66, v66, v66 quad_perm:[2,3,0,1] row_mask:0xf bank_mask:0xf bound_ctrl:1
	v_pk_fma_f32 v[92:93], v[142:143], v[136:137], v[92:93] op_sel_hi:[0,1,1]
	v_add_f32_dpp v60, v60, v60 row_half_mirror row_mask:0xf bank_mask:0xf bound_ctrl:1
	v_add_f32_dpp v62, v62, v62 row_half_mirror row_mask:0xf bank_mask:0xf bound_ctrl:1
	v_add_f32_dpp v64, v64, v64 row_half_mirror row_mask:0xf bank_mask:0xf bound_ctrl:1
	v_add_f32_dpp v66, v66, v66 row_half_mirror row_mask:0xf bank_mask:0xf bound_ctrl:1
	v_cmp_eq_u32_e32 vcc, 1, v68
	v_add_f32_dpp v60, v60, v60 row_mirror row_mask:0xf bank_mask:0xf bound_ctrl:1
	v_add_f32_dpp v62, v62, v62 row_mirror row_mask:0xf bank_mask:0xf bound_ctrl:1
	v_add_f32_dpp v64, v64, v64 row_mirror row_mask:0xf bank_mask:0xf bound_ctrl:1
	v_add_f32_dpp v66, v66, v66 row_mirror row_mask:0xf bank_mask:0xf bound_ctrl:1
	v_pk_fma_f32 v[94:95], v[130:131], v[60:61], v[94:95] op_sel_hi:[1,0,1] neg_lo:[1,0,0] neg_hi:[1,0,0]
	v_pk_fma_f32 v[92:93], v[132:133], v[60:61], v[92:93] op_sel_hi:[1,0,1] neg_lo:[1,0,0] neg_hi:[1,0,0]
	v_pk_mul_f32 v[238:239], v[130:131], v[62:63] op_sel_hi:[1,0]
	v_pk_mul_f32 v[240:241], v[132:133], v[62:63] op_sel_hi:[1,0]
	v_cndmask_b32_e32 v72, v72, v64, vcc
	v_cndmask_b32_e32 v73, v73, v66, vcc
	v_pk_mul_f32 v[64:65], v[138:139], v[94:95]
	v_pk_fma_f32 v[88:89], v[88:89], v[122:123], v[238:239] neg_lo:[0,0,1] neg_hi:[0,0,1]
	v_pk_fma_f32 v[90:91], v[90:91], v[124:125], v[240:241] neg_lo:[0,0,1] neg_hi:[0,0,1]
	v_pk_fma_f32 v[64:65], v[140:141], v[92:93], v[64:65]
	v_pk_mul_f32 v[66:67], v[138:139], v[88:89]
	v_pk_fma_f32 v[66:67], v[140:141], v[90:91], v[66:67]
	ds_read_b128 v[220:223], v74 offset:30208
	ds_read_b128 v[216:219], v74 offset:29952
	ds_read_b128 v[228:231], v74 offset:30720
	ds_read_b32 v236, v75 offset:31232
	ds_read_b128 v[224:227], v74 offset:30464
	ds_read_b128 v[232:235], v74 offset:30976
	s_waitcnt lgkmcnt(6)
; template <bool DUAL>
; __device__ __forceinline__ void rwkv_tile(const Params& p, int l, int tile, unsigned char* smem) {
;     ...
; #pragma unroll 2
;       for (int i = 0; i < 32; ++i) {
;         const int inx = (i + 1) & 31;
;         const float4 nw4 = *(const float4*)(rp + inx * 384), nkk4 = *(const float4*)(rp + inx * 384 + 64), nkb4 = *(const float4*)(rp + inx * 384 + 128);
;         const float4 nkd4 = *(const float4*)(rp + inx * 384 + 192), nr4 = *(const float4*)(rp + inx * 384 + 256);
;         const float nv = vp[inx * 384];
;         v2f t = sA * (v2f){kk4.x, kk4.y};
;         t = sB * (v2f){kk4.z, kk4.w} + t;
;         float sa = t.x + t.y, ia = 0.f;
;         if (DUAL) {
;           v2f ti = iA * (v2f){kk4.x, kk4.y};
;           ti = iB * (v2f){kk4.z, kk4.w} + ti;
;           ia = ti.x + ti.y;
;           sa += dppf<0xB1>(sa); ia += dppf<0xB1>(ia);
;           sa += dppf<0x4E>(sa); ia += dppf<0x4E>(ia);
;           sa += dppf<0x141>(sa); ia += dppf<0x141>(ia);
;           sa += dppf<0x140>(sa); ia += dppf<0x140>(ia);
;         } else {
;           sa = sum16(sa);
;         }
;         v2f cA = sA * (v2f){w4.x, w4.y} + (v2f){kd4.x, kd4.y} * v;
;         v2f cB = sB * (v2f){w4.z, w4.w} + (v2f){kd4.z, kd4.w} * v;
;         sA = cA - (v2f){kb4.x, kb4.y} * sa;
;         sB = cB - (v2f){kb4.z, kb4.w} * sa;
;         v2f u = sA * (v2f){r4.x, r4.y};
;         u = sB * (v2f){r4.z, r4.w} + u;
;         float y = u.x + u.y, g = 0.f;
;         if (DUAL) {
;           iA = iA * (v2f){w4.x, w4.y} - (v2f){kb4.x, kb4.y} * ia;
;           iB = iB * (v2f){w4.z, w4.w} - (v2f){kb4.z, kb4.w} * ia;
;           v2f ui = iA * (v2f){r4.x, r4.y};
;           ui = iB * (v2f){r4.z, r4.w} + ui;
;           g = ui.x + ui.y;
;           y += dppf<0xB1>(y); g += dppf<0xB1>(g);
;           y += dppf<0x4E>(y); g += dppf<0x4E>(g);
;           y += dppf<0x141>(y); g += dppf<0x141>(g);
;           y += dppf<0x140>(y); g += dppf<0x140>(g);
;           if (fr == (i & 15)) gkeep = g;
;         } else {
;           y = sum16(y);
;         }
;         if (fr == (i & 15)) ykeep = y;
	v_pk_mul_f32 v[60:61], v[94:95], v[148:149]
	v_pk_mul_f32 v[62:63], v[88:89], v[148:149]
	v_pk_fma_f32 v[60:61], v[92:93], v[150:151], v[60:61]
	v_pk_fma_f32 v[62:63], v[90:91], v[150:151], v[62:63]
	v_add_f32_e32 v64, v64, v65
	v_add_f32_e32 v66, v66, v67
	v_add_f32_e32 v60, v60, v61
	v_add_f32_e32 v62, v62, v63
	v_pk_mul_f32 v[94:95], v[94:95], v[144:145]
	v_pk_mul_f32 v[92:93], v[92:93], v[146:147]
	v_add_f32_dpp v60, v60, v60 quad_perm:[1,0,3,2] row_mask:0xf bank_mask:0xf bound_ctrl:1
	v_add_f32_dpp v62, v62, v62 quad_perm:[1,0,3,2] row_mask:0xf bank_mask:0xf bound_ctrl:1
	v_add_f32_dpp v64, v64, v64 quad_perm:[1,0,3,2] row_mask:0xf bank_mask:0xf bound_ctrl:1
	v_add_f32_dpp v66, v66, v66 quad_perm:[1,0,3,2] row_mask:0xf bank_mask:0xf bound_ctrl:1
	v_pk_fma_f32 v[94:95], v[96:97], v[156:157], v[94:95] op_sel_hi:[0,1,1]
	v_add_f32_dpp v60, v60, v60 quad_perm:[2,3,0,1] row_mask:0xf bank_mask:0xf bound_ctrl:1
	v_add_f32_dpp v62, v62, v62 quad_perm:[2,3,0,1] row_mask:0xf bank_mask:0xf bound_ctrl:1
	v_add_f32_dpp v64, v64, v64 quad_perm:[2,3,0,1] row_mask:0xf bank_mask:0xf bound_ctrl:1
	v_add_f32_dpp v66, v66, v66 quad_perm:[2,3,0,1] row_mask:0xf bank_mask:0xf bound_ctrl:1
	v_pk_fma_f32 v[92:93], v[96:97], v[158:159], v[92:93] op_sel_hi:[0,1,1]
	v_add_f32_dpp v60, v60, v60 row_half_mirror row_mask:0xf bank_mask:0xf bound_ctrl:1
	v_add_f32_dpp v62, v62, v62 row_half_mirror row_mask:0xf bank_mask:0xf bound_ctrl:1
	v_add_f32_dpp v64, v64, v64 row_half_mirror row_mask:0xf bank_mask:0xf bound_ctrl:1
	v_add_f32_dpp v66, v66, v66 row_half_mirror row_mask:0xf bank_mask:0xf bound_ctrl:1
	v_cmp_eq_u32_e32 vcc, 2, v68
	v_add_f32_dpp v60, v60, v60 row_mirror row_mask:0xf bank_mask:0xf bound_ctrl:1
	v_add_f32_dpp v62, v62, v62 row_mirror row_mask:0xf bank_mask:0xf bound_ctrl:1
	v_add_f32_dpp v64, v64, v64 row_mirror row_mask:0xf bank_mask:0xf bound_ctrl:1
	v_add_f32_dpp v66, v66, v66 row_mirror row_mask:0xf bank_mask:0xf bound_ctrl:1
	v_pk_fma_f32 v[94:95], v[152:153], v[60:61], v[94:95] op_sel_hi:[1,0,1] neg_lo:[1,0,0] neg_hi:[1,0,0]
	v_pk_fma_f32 v[92:93], v[154:155], v[60:61], v[92:93] op_sel_hi:[1,0,1] neg_lo:[1,0,0] neg_hi:[1,0,0]
	v_pk_mul_f32 v[238:239], v[152:153], v[62:63] op_sel_hi:[1,0]
	v_pk_mul_f32 v[240:241], v[154:155], v[62:63] op_sel_hi:[1,0]
	v_cndmask_b32_e32 v72, v72, v64, vcc
	v_cndmask_b32_e32 v73, v73, v66, vcc
	v_pk_mul_f32 v[64:65], v[160:161], v[94:95]
	v_pk_fma_f32 v[88:89], v[88:89], v[144:145], v[238:239] neg_lo:[0,0,1] neg_hi:[0,0,1]
	v_pk_fma_f32 v[90:91], v[90:91], v[146:147], v[240:241] neg_lo:[0,0,1] neg_hi:[0,0,1]
	v_pk_fma_f32 v[64:65], v[162:163], v[92:93], v[64:65]
	v_pk_mul_f32 v[66:67], v[160:161], v[88:89]
	v_pk_fma_f32 v[66:67], v[162:163], v[90:91], v[66:67]
	ds_read_b128 v[126:129], v74 offset:31744
	ds_read_b128 v[122:125], v74 offset:31488
	ds_read_b128 v[134:137], v74 offset:32256
	ds_read_b32 v142, v75 offset:32768
	ds_read_b128 v[130:133], v74 offset:32000
	ds_read_b128 v[138:141], v74 offset:32512
	s_waitcnt lgkmcnt(6)
	v_pk_mul_f32 v[60:61], v[94:95], v[220:221]
	v_pk_mul_f32 v[62:63], v[88:89], v[220:221]
	v_pk_fma_f32 v[60:61], v[92:93], v[222:223], v[60:61]
	v_pk_fma_f32 v[62:63], v[90:91], v[222:223], v[62:63]
	v_add_f32_e32 v64, v64, v65
	v_add_f32_e32 v66, v66, v67
	v_add_f32_e32 v60, v60, v61
	v_add_f32_e32 v62, v62, v63
	v_pk_mul_f32 v[94:95], v[94:95], v[216:217]
	v_pk_mul_f32 v[92:93], v[92:93], v[218:219]
	v_add_f32_dpp v60, v60, v60 quad_perm:[1,0,3,2] row_mask:0xf bank_mask:0xf bound_ctrl:1
	v_add_f32_dpp v62, v62, v62 quad_perm:[1,0,3,2] row_mask:0xf bank_mask:0xf bound_ctrl:1
	v_add_f32_dpp v64, v64, v64 quad_perm:[1,0,3,2] row_mask:0xf bank_mask:0xf bound_ctrl:1
	v_add_f32_dpp v66, v66, v66 quad_perm:[1,0,3,2] row_mask:0xf bank_mask:0xf bound_ctrl:1
	v_pk_fma_f32 v[94:95], v[236:237], v[228:229], v[94:95] op_sel_hi:[0,1,1]
	v_add_f32_dpp v60, v60, v60 quad_perm:[2,3,0,1] row_mask:0xf bank_mask:0xf bound_ctrl:1
	v_add_f32_dpp v62, v62, v62 quad_perm:[2,3,0,1] row_mask:0xf bank_mask:0xf bound_ctrl:1
	v_add_f32_dpp v64, v64, v64 quad_perm:[2,3,0,1] row_mask:0xf bank_mask:0xf bound_ctrl:1
	v_add_f32_dpp v66, v66, v66 quad_perm:[2,3,0,1] row_mask:0xf bank_mask:0xf bound_ctrl:1
	v_pk_fma_f32 v[92:93], v[236:237], v[230:231], v[92:93] op_sel_hi:[0,1,1]
	v_add_f32_dpp v60, v60, v60 row_half_mirror row_mask:0xf bank_mask:0xf bound_ctrl:1
	v_add_f32_dpp v62, v62, v62 row_half_mirror row_mask:0xf bank_mask:0xf bound_ctrl:1
	v_add_f32_dpp v64, v64, v64 row_half_mirror row_mask:0xf bank_mask:0xf bound_ctrl:1
	v_add_f32_dpp v66, v66, v66 row_half_mirror row_mask:0xf bank_mask:0xf bound_ctrl:1
	v_cmp_eq_u32_e32 vcc, 3, v68
	v_add_f32_dpp v60, v60, v60 row_mirror row_mask:0xf bank_mask:0xf bound_ctrl:1
	v_add_f32_dpp v62, v62, v62 row_mirror row_mask:0xf bank_mask:0xf bound_ctrl:1
	v_add_f32_dpp v64, v64, v64 row_mirror row_mask:0xf bank_mask:0xf bound_ctrl:1
	v_add_f32_dpp v66, v66, v66 row_mirror row_mask:0xf bank_mask:0xf bound_ctrl:1
	v_pk_fma_f32 v[94:95], v[224:225], v[60:61], v[94:95] op_sel_hi:[1,0,1] neg_lo:[1,0,0] neg_hi:[1,0,0]
	v_pk_fma_f32 v[92:93], v[226:227], v[60:61], v[92:93] op_sel_hi:[1,0,1] neg_lo:[1,0,0] neg_hi:[1,0,0]
	v_pk_mul_f32 v[238:239], v[224:225], v[62:63] op_sel_hi:[1,0]
	v_pk_mul_f32 v[240:241], v[226:227], v[62:63] op_sel_hi:[1,0]
	v_cndmask_b32_e32 v72, v72, v64, vcc
	v_cndmask_b32_e32 v73, v73, v66, vcc
	v_pk_mul_f32 v[64:65], v[232:233], v[94:95]
	v_pk_fma_f32 v[88:89], v[88:89], v[216:217], v[238:239] neg_lo:[0,0,1] neg_hi:[0,0,1]
	v_pk_fma_f32 v[90:91], v[90:91], v[218:219], v[240:241] neg_lo:[0,0,1] neg_hi:[0,0,1]
	v_pk_fma_f32 v[64:65], v[234:235], v[92:93], v[64:65]
	v_pk_mul_f32 v[66:67], v[232:233], v[88:89]
	v_pk_fma_f32 v[66:67], v[234:235], v[90:91], v[66:67]
	ds_read_b128 v[148:151], v74 offset:33280
	ds_read_b128 v[144:147], v74 offset:33024
	ds_read_b128 v[156:159], v74 offset:33792
	ds_read_b32 v96, v75 offset:34304
	ds_read_b128 v[152:155], v74 offset:33536
	ds_read_b128 v[160:163], v74 offset:34048
	s_waitcnt lgkmcnt(6)
; template <bool DUAL>
; __device__ __forceinline__ void rwkv_tile(const Params& p, int l, int tile, unsigned char* smem) {
;     ...
; #pragma unroll 2
;       for (int i = 0; i < 32; ++i) {
;         const int inx = (i + 1) & 31;
;         const float4 nw4 = *(const float4*)(rp + inx * 384), nkk4 = *(const float4*)(rp + inx * 384 + 64), nkb4 = *(const float4*)(rp + inx * 384 + 128);
;         const float4 nkd4 = *(const float4*)(rp + inx * 384 + 192), nr4 = *(const float4*)(rp + inx * 384 + 256);
;         const float nv = vp[inx * 384];
;         v2f t = sA * (v2f){kk4.x, kk4.y};
;         t = sB * (v2f){kk4.z, kk4.w} + t;
;         float sa = t.x + t.y, ia = 0.f;
;         if (DUAL) {
;           v2f ti = iA * (v2f){kk4.x, kk4.y};
;           ti = iB * (v2f){kk4.z, kk4.w} + ti;
;           ia = ti.x + ti.y;
;           sa += dppf<0xB1>(sa); ia += dppf<0xB1>(ia);
;           sa += dppf<0x4E>(sa); ia += dppf<0x4E>(ia);
;           sa += dppf<0x141>(sa); ia += dppf<0x141>(ia);
;           sa += dppf<0x140>(sa); ia += dppf<0x140>(ia);
;         } else {
;           sa = sum16(sa);
;         }
;         v2f cA = sA * (v2f){w4.x, w4.y} + (v2f){kd4.x, kd4.y} * v;
;         v2f cB = sB * (v2f){w4.z, w4.w} + (v2f){kd4.z, kd4.w} * v;
;         sA = cA - (v2f){kb4.x, kb4.y} * sa;
;         sB = cB - (v2f){kb4.z, kb4.w} * sa;
;         v2f u = sA * (v2f){r4.x, r4.y};
;         u = sB * (v2f){r4.z, r4.w} + u;
;         float y = u.x + u.y, g = 0.f;
;         if (DUAL) {
;           iA = iA * (v2f){w4.x, w4.y} - (v2f){kb4.x, kb4.y} * ia;
;           iB = iB * (v2f){w4.z, w4.w} - (v2f){kb4.z, kb4.w} * ia;
;           v2f ui = iA * (v2f){r4.x, r4.y};
;           ui = iB * (v2f){r4.z, r4.w} + ui;
;           g = ui.x + ui.y;
;           y += dppf<0xB1>(y); g += dppf<0xB1>(g);
;           y += dppf<0x4E>(y); g += dppf<0x4E>(g);
;           y += dppf<0x141>(y); g += dppf<0x141>(g);
;           y += dppf<0x140>(y); g += dppf<0x140>(g);
;           if (fr == (i & 15)) gkeep = g;
;         } else {
;           y = sum16(y);
;         }
;         if (fr == (i & 15)) ykeep = y;
;         if ((i & 15) == 15) {
;           const int ii = (i & 16) + fr;
;           const int ri = (d == 0) ? ii + 1 : 32 - ii;
;           const int pi = plo - 1 + ri;
;           p.yR[((size_t)d * TOK + rowbase + pi) * 256 + h * 64 + row] = f2bf(ykeep);
	v_pk_mul_f32 v[60:61], v[94:95], v[126:127]
	v_pk_mul_f32 v[62:63], v[88:89], v[126:127]
	v_pk_fma_f32 v[60:61], v[92:93], v[128:129], v[60:61]
	v_pk_fma_f32 v[62:63], v[90:91], v[128:129], v[62:63]
	v_add_f32_e32 v64, v64, v65
	v_add_f32_e32 v66, v66, v67
	v_add_f32_e32 v60, v60, v61
	v_add_f32_e32 v62, v62, v63
	v_pk_mul_f32 v[94:95], v[94:95], v[122:123]
	v_pk_mul_f32 v[92:93], v[92:93], v[124:125]
	v_add_f32_dpp v60, v60, v60 quad_perm:[1,0,3,2] row_mask:0xf bank_mask:0xf bound_ctrl:1
	v_add_f32_dpp v62, v62, v62 quad_perm:[1,0,3,2] row_mask:0xf bank_mask:0xf bound_ctrl:1
	v_add_f32_dpp v64, v64, v64 quad_perm:[1,0,3,2] row_mask:0xf bank_mask:0xf bound_ctrl:1
	v_add_f32_dpp v66, v66, v66 quad_perm:[1,0,3,2] row_mask:0xf bank_mask:0xf bound_ctrl:1
	v_pk_fma_f32 v[94:95], v[142:143], v[134:135], v[94:95] op_sel_hi:[0,1,1]
	v_add_f32_dpp v60, v60, v60 quad_perm:[2,3,0,1] row_mask:0xf bank_mask:0xf bound_ctrl:1
	v_add_f32_dpp v62, v62, v62 quad_perm:[2,3,0,1] row_mask:0xf bank_mask:0xf bound_ctrl:1
	v_add_f32_dpp v64, v64, v64 quad_perm:[2,3,0,1] row_mask:0xf bank_mask:0xf bound_ctrl:1
	v_add_f32_dpp v66, v66, v66 quad_perm:[2,3,0,1] row_mask:0xf bank_mask:0xf bound_ctrl:1
	v_pk_fma_f32 v[92:93], v[142:143], v[136:137], v[92:93] op_sel_hi:[0,1,1]
	v_add_f32_dpp v60, v60, v60 row_half_mirror row_mask:0xf bank_mask:0xf bound_ctrl:1
	v_add_f32_dpp v62, v62, v62 row_half_mirror row_mask:0xf bank_mask:0xf bound_ctrl:1
	v_add_f32_dpp v64, v64, v64 row_half_mirror row_mask:0xf bank_mask:0xf bound_ctrl:1
	v_add_f32_dpp v66, v66, v66 row_half_mirror row_mask:0xf bank_mask:0xf bound_ctrl:1
	v_cmp_eq_u32_e32 vcc, 4, v68
	v_add_f32_dpp v60, v60, v60 row_mirror row_mask:0xf bank_mask:0xf bound_ctrl:1
	v_add_f32_dpp v62, v62, v62 row_mirror row_mask:0xf bank_mask:0xf bound_ctrl:1
	v_add_f32_dpp v64, v64, v64 row_mirror row_mask:0xf bank_mask:0xf bound_ctrl:1
	v_add_f32_dpp v66, v66, v66 row_mirror row_mask:0xf bank_mask:0xf bound_ctrl:1
	v_pk_fma_f32 v[94:95], v[130:131], v[60:61], v[94:95] op_sel_hi:[1,0,1] neg_lo:[1,0,0] neg_hi:[1,0,0]
	v_pk_fma_f32 v[92:93], v[132:133], v[60:61], v[92:93] op_sel_hi:[1,0,1] neg_lo:[1,0,0] neg_hi:[1,0,0]
	v_pk_mul_f32 v[238:239], v[130:131], v[62:63] op_sel_hi:[1,0]
	v_pk_mul_f32 v[240:241], v[132:133], v[62:63] op_sel_hi:[1,0]
	v_cndmask_b32_e32 v72, v72, v64, vcc
	v_cndmask_b32_e32 v73, v73, v66, vcc
	s_cmp_eq_u32 s55, 2
	s_cbranch_scc1 .Lrw_du_st0
.Lrw_du_back:
	v_pk_mul_f32 v[64:65], v[138:139], v[94:95]
	v_pk_fma_f32 v[88:89], v[88:89], v[122:123], v[238:239] neg_lo:[0,0,1] neg_hi:[0,0,1]
	v_pk_fma_f32 v[90:91], v[90:91], v[124:125], v[240:241] neg_lo:[0,0,1] neg_hi:[0,0,1]
	v_pk_fma_f32 v[64:65], v[140:141], v[92:93], v[64:65]
	v_pk_mul_f32 v[66:67], v[138:139], v[88:89]
	v_pk_fma_f32 v[66:67], v[140:141], v[90:91], v[66:67]
	ds_read_b128 v[220:223], v74 offset:34816
	ds_read_b128 v[216:219], v74 offset:34560
	ds_read_b128 v[228:231], v74 offset:35328
	ds_read_b32 v236, v75 offset:35840
	ds_read_b128 v[224:227], v74 offset:35072
	ds_read_b128 v[232:235], v74 offset:35584
	s_waitcnt lgkmcnt(6)
	v_pk_mul_f32 v[60:61], v[94:95], v[148:149]
	v_pk_mul_f32 v[62:63], v[88:89], v[148:149]
	v_pk_fma_f32 v[60:61], v[92:93], v[150:151], v[60:61]
	v_pk_fma_f32 v[62:63], v[90:91], v[150:151], v[62:63]
	v_add_f32_e32 v64, v64, v65
	v_add_f32_e32 v66, v66, v67
	v_add_f32_e32 v60, v60, v61
	v_add_f32_e32 v62, v62, v63
	v_pk_mul_f32 v[94:95], v[94:95], v[144:145]
	v_pk_mul_f32 v[92:93], v[92:93], v[146:147]
	v_add_f32_dpp v60, v60, v60 quad_perm:[1,0,3,2] row_mask:0xf bank_mask:0xf bound_ctrl:1
	v_add_f32_dpp v62, v62, v62 quad_perm:[1,0,3,2] row_mask:0xf bank_mask:0xf bound_ctrl:1
	v_add_f32_dpp v64, v64, v64 quad_perm:[1,0,3,2] row_mask:0xf bank_mask:0xf bound_ctrl:1
	v_add_f32_dpp v66, v66, v66 quad_perm:[1,0,3,2] row_mask:0xf bank_mask:0xf bound_ctrl:1
	v_pk_fma_f32 v[94:95], v[96:97], v[156:157], v[94:95] op_sel_hi:[0,1,1]
	v_add_f32_dpp v60, v60, v60 quad_perm:[2,3,0,1] row_mask:0xf bank_mask:0xf bound_ctrl:1
	v_add_f32_dpp v62, v62, v62 quad_perm:[2,3,0,1] row_mask:0xf bank_mask:0xf bound_ctrl:1
	v_add_f32_dpp v64, v64, v64 quad_perm:[2,3,0,1] row_mask:0xf bank_mask:0xf bound_ctrl:1
	v_add_f32_dpp v66, v66, v66 quad_perm:[2,3,0,1] row_mask:0xf bank_mask:0xf bound_ctrl:1
	v_pk_fma_f32 v[92:93], v[96:97], v[158:159], v[92:93] op_sel_hi:[0,1,1]
	v_add_f32_dpp v60, v60, v60 row_half_mirror row_mask:0xf bank_mask:0xf bound_ctrl:1
	v_add_f32_dpp v62, v62, v62 row_half_mirror row_mask:0xf bank_mask:0xf bound_ctrl:1
	v_add_f32_dpp v64, v64, v64 row_half_mirror row_mask:0xf bank_mask:0xf bound_ctrl:1
	v_add_f32_dpp v66, v66, v66 row_half_mirror row_mask:0xf bank_mask:0xf bound_ctrl:1
	v_cmp_eq_u32_e32 vcc, 5, v68
	v_add_f32_dpp v60, v60, v60 row_mirror row_mask:0xf bank_mask:0xf bound_ctrl:1
	v_add_f32_dpp v62, v62, v62 row_mirror row_mask:0xf bank_mask:0xf bound_ctrl:1
	v_add_f32_dpp v64, v64, v64 row_mirror row_mask:0xf bank_mask:0xf bound_ctrl:1
	v_add_f32_dpp v66, v66, v66 row_mirror row_mask:0xf bank_mask:0xf bound_ctrl:1
	v_pk_fma_f32 v[94:95], v[152:153], v[60:61], v[94:95] op_sel_hi:[1,0,1] neg_lo:[1,0,0] neg_hi:[1,0,0]
	v_pk_fma_f32 v[92:93], v[154:155], v[60:61], v[92:93] op_sel_hi:[1,0,1] neg_lo:[1,0,0] neg_hi:[1,0,0]
	v_pk_mul_f32 v[238:239], v[152:153], v[62:63] op_sel_hi:[1,0]
	v_pk_mul_f32 v[240:241], v[154:155], v[62:63] op_sel_hi:[1,0]
	v_cndmask_b32_e32 v72, v72, v64, vcc
	v_cndmask_b32_e32 v73, v73, v66, vcc
	v_pk_mul_f32 v[64:65], v[160:161], v[94:95]
	v_pk_fma_f32 v[88:89], v[88:89], v[144:145], v[238:239] neg_lo:[0,0,1] neg_hi:[0,0,1]
	v_pk_fma_f32 v[90:91], v[90:91], v[146:147], v[240:241] neg_lo:[0,0,1] neg_hi:[0,0,1]
	v_pk_fma_f32 v[64:65], v[162:163], v[92:93], v[64:65]
	v_pk_mul_f32 v[66:67], v[160:161], v[88:89]
	v_pk_fma_f32 v[66:67], v[162:163], v[90:91], v[66:67]
	ds_read_b128 v[126:129], v74 offset:36352
	ds_read_b128 v[122:125], v74 offset:36096
	ds_read_b128 v[134:137], v74 offset:36864
	ds_read_b32 v142, v75 offset:37376
	ds_read_b128 v[130:133], v74 offset:36608
	ds_read_b128 v[138:141], v74 offset:37120
	v_add_u32_e32 v74, 0x2400, v74
	v_add_u32_e32 v75, 0x2400, v75
	v_add_u32_e32 v68, -6, v68
	v_and_b32_e32 v68, 15, v68
	s_add_i32 s55, s55, 1
	s_cmp_lg_u32 s55, 5
	s_cbranch_scc1 .Lrw_du_loop
; template <bool DUAL>
; __device__ __forceinline__ void rwkv_tile(const Params& p, int l, int tile, unsigned char* smem) {
;     ...
; #pragma unroll 2
;       for (int i = 0; i < 32; ++i) {
;         const int inx = (i + 1) & 31;
;         const float4 nw4 = *(const float4*)(rp + inx * 384), nkk4 = *(const float4*)(rp + inx * 384 + 64), nkb4 = *(const float4*)(rp + inx * 384 + 128);
;         const float4 nkd4 = *(const float4*)(rp + inx * 384 + 192), nr4 = *(const float4*)(rp + inx * 384 + 256);
;         const float nv = vp[inx * 384];
;         v2f t = sA * (v2f){kk4.x, kk4.y};
;         t = sB * (v2f){kk4.z, kk4.w} + t;
;         float sa = t.x + t.y, ia = 0.f;
;         if (DUAL) {
;           v2f ti = iA * (v2f){kk4.x, kk4.y};
;           ti = iB * (v2f){kk4.z, kk4.w} + ti;
;           ia = ti.x + ti.y;
;           sa += dppf<0xB1>(sa); ia += dppf<0xB1>(ia);
;           sa += dppf<0x4E>(sa); ia += dppf<0x4E>(ia);
;           sa += dppf<0x141>(sa); ia += dppf<0x141>(ia);
;           sa += dppf<0x140>(sa); ia += dppf<0x140>(ia);
;         } else {
;           sa = sum16(sa);
;         }
;         v2f cA = sA * (v2f){w4.x, w4.y} + (v2f){kd4.x, kd4.y} * v;
;         v2f cB = sB * (v2f){w4.z, w4.w} + (v2f){kd4.z, kd4.w} * v;
;         sA = cA - (v2f){kb4.x, kb4.y} * sa;
;         sB = cB - (v2f){kb4.z, kb4.w} * sa;
;         v2f u = sA * (v2f){r4.x, r4.y};
;         u = sB * (v2f){r4.z, r4.w} + u;
;         float y = u.x + u.y, g = 0.f;
;         if (DUAL) {
;           iA = iA * (v2f){w4.x, w4.y} - (v2f){kb4.x, kb4.y} * ia;
;           iB = iB * (v2f){w4.z, w4.w} - (v2f){kb4.z, kb4.w} * ia;
;           v2f ui = iA * (v2f){r4.x, r4.y};
;           ui = iB * (v2f){r4.z, r4.w} + ui;
;           g = ui.x + ui.y;
;           y += dppf<0xB1>(y); g += dppf<0xB1>(g);
;           y += dppf<0x4E>(y); g += dppf<0x4E>(g);
;           y += dppf<0x141>(y); g += dppf<0x141>(g);
;           y += dppf<0x140>(y); g += dppf<0x140>(g);
;           if (fr == (i & 15)) gkeep = g;
;         } else {
;           y = sum16(y);
;         }
;         if (fr == (i & 15)) ykeep = y;
;         if ((i & 15) == 15) {
;           const int ii = (i & 16) + fr;
;           const int ri = (d == 0) ? ii + 1 : 32 - ii;
;           const int pi = plo - 1 + ri;
;           p.yR[((size_t)d * TOK + rowbase + pi) * 256 + h * 64 + row] = f2bf(ykeep);
	s_waitcnt lgkmcnt(6)
	v_pk_mul_f32 v[60:61], v[94:95], v[220:221]
	v_pk_mul_f32 v[62:63], v[88:89], v[220:221]
	v_pk_fma_f32 v[60:61], v[92:93], v[222:223], v[60:61]
	v_pk_fma_f32 v[62:63], v[90:91], v[222:223], v[62:63]
	v_add_f32_e32 v64, v64, v65
	v_add_f32_e32 v66, v66, v67
	v_add_f32_e32 v60, v60, v61
	v_add_f32_e32 v62, v62, v63
	v_pk_mul_f32 v[94:95], v[94:95], v[216:217]
	v_pk_mul_f32 v[92:93], v[92:93], v[218:219]
	v_add_f32_dpp v60, v60, v60 quad_perm:[1,0,3,2] row_mask:0xf bank_mask:0xf bound_ctrl:1
	v_add_f32_dpp v62, v62, v62 quad_perm:[1,0,3,2] row_mask:0xf bank_mask:0xf bound_ctrl:1
	v_add_f32_dpp v64, v64, v64 quad_perm:[1,0,3,2] row_mask:0xf bank_mask:0xf bound_ctrl:1
	v_add_f32_dpp v66, v66, v66 quad_perm:[1,0,3,2] row_mask:0xf bank_mask:0xf bound_ctrl:1
	v_pk_fma_f32 v[94:95], v[236:237], v[228:229], v[94:95] op_sel_hi:[0,1,1]
	v_add_f32_dpp v60, v60, v60 quad_perm:[2,3,0,1] row_mask:0xf bank_mask:0xf bound_ctrl:1
	v_add_f32_dpp v62, v62, v62 quad_perm:[2,3,0,1] row_mask:0xf bank_mask:0xf bound_ctrl:1
	v_add_f32_dpp v64, v64, v64 quad_perm:[2,3,0,1] row_mask:0xf bank_mask:0xf bound_ctrl:1
	v_add_f32_dpp v66, v66, v66 quad_perm:[2,3,0,1] row_mask:0xf bank_mask:0xf bound_ctrl:1
	v_pk_fma_f32 v[92:93], v[236:237], v[230:231], v[92:93] op_sel_hi:[0,1,1]
	v_add_f32_dpp v60, v60, v60 row_half_mirror row_mask:0xf bank_mask:0xf bound_ctrl:1
	v_add_f32_dpp v62, v62, v62 row_half_mirror row_mask:0xf bank_mask:0xf bound_ctrl:1
	v_add_f32_dpp v64, v64, v64 row_half_mirror row_mask:0xf bank_mask:0xf bound_ctrl:1
	v_add_f32_dpp v66, v66, v66 row_half_mirror row_mask:0xf bank_mask:0xf bound_ctrl:1
	v_cmp_eq_u32_e32 vcc, 0, v68
	v_add_f32_dpp v60, v60, v60 row_mirror row_mask:0xf bank_mask:0xf bound_ctrl:1
	v_add_f32_dpp v62, v62, v62 row_mirror row_mask:0xf bank_mask:0xf bound_ctrl:1
	v_add_f32_dpp v64, v64, v64 row_mirror row_mask:0xf bank_mask:0xf bound_ctrl:1
	v_add_f32_dpp v66, v66, v66 row_mirror row_mask:0xf bank_mask:0xf bound_ctrl:1
	v_pk_fma_f32 v[94:95], v[224:225], v[60:61], v[94:95] op_sel_hi:[1,0,1] neg_lo:[1,0,0] neg_hi:[1,0,0]
	v_pk_fma_f32 v[92:93], v[226:227], v[60:61], v[92:93] op_sel_hi:[1,0,1] neg_lo:[1,0,0] neg_hi:[1,0,0]
	v_pk_mul_f32 v[238:239], v[224:225], v[62:63] op_sel_hi:[1,0]
	v_pk_mul_f32 v[240:241], v[226:227], v[62:63] op_sel_hi:[1,0]
	v_cndmask_b32_e32 v72, v72, v64, vcc
	v_cndmask_b32_e32 v73, v73, v66, vcc
	v_pk_mul_f32 v[64:65], v[232:233], v[94:95]
	v_pk_fma_f32 v[88:89], v[88:89], v[216:217], v[238:239] neg_lo:[0,0,1] neg_hi:[0,0,1]
	v_pk_fma_f32 v[90:91], v[90:91], v[218:219], v[240:241] neg_lo:[0,0,1] neg_hi:[0,0,1]
	v_pk_fma_f32 v[64:65], v[234:235], v[92:93], v[64:65]
	v_pk_mul_f32 v[66:67], v[232:233], v[88:89]
	v_pk_fma_f32 v[66:67], v[234:235], v[90:91], v[66:67]
	s_waitcnt lgkmcnt(0)
	v_pk_mul_f32 v[60:61], v[94:95], v[126:127]
	v_pk_mul_f32 v[62:63], v[88:89], v[126:127]
	v_pk_fma_f32 v[60:61], v[92:93], v[128:129], v[60:61]
	v_pk_fma_f32 v[62:63], v[90:91], v[128:129], v[62:63]
	v_add_f32_e32 v64, v64, v65
	v_add_f32_e32 v66, v66, v67
	v_add_f32_e32 v60, v60, v61
	v_add_f32_e32 v62, v62, v63
	v_pk_mul_f32 v[94:95], v[94:95], v[122:123]
	v_pk_mul_f32 v[92:93], v[92:93], v[124:125]
	v_add_f32_dpp v60, v60, v60 quad_perm:[1,0,3,2] row_mask:0xf bank_mask:0xf bound_ctrl:1
	v_add_f32_dpp v62, v62, v62 quad_perm:[1,0,3,2] row_mask:0xf bank_mask:0xf bound_ctrl:1
	v_add_f32_dpp v64, v64, v64 quad_perm:[1,0,3,2] row_mask:0xf bank_mask:0xf bound_ctrl:1
	v_add_f32_dpp v66, v66, v66 quad_perm:[1,0,3,2] row_mask:0xf bank_mask:0xf bound_ctrl:1
	v_pk_fma_f32 v[94:95], v[142:143], v[134:135], v[94:95] op_sel_hi:[0,1,1]
	v_add_f32_dpp v60, v60, v60 quad_perm:[2,3,0,1] row_mask:0xf bank_mask:0xf bound_ctrl:1
	v_add_f32_dpp v62, v62, v62 quad_perm:[2,3,0,1] row_mask:0xf bank_mask:0xf bound_ctrl:1
	v_add_f32_dpp v64, v64, v64 quad_perm:[2,3,0,1] row_mask:0xf bank_mask:0xf bound_ctrl:1
	v_add_f32_dpp v66, v66, v66 quad_perm:[2,3,0,1] row_mask:0xf bank_mask:0xf bound_ctrl:1
	v_pk_fma_f32 v[92:93], v[142:143], v[136:137], v[92:93] op_sel_hi:[0,1,1]
	v_add_f32_dpp v60, v60, v60 row_half_mirror row_mask:0xf bank_mask:0xf bound_ctrl:1
	v_add_f32_dpp v62, v62, v62 row_half_mirror row_mask:0xf bank_mask:0xf bound_ctrl:1
	v_add_f32_dpp v64, v64, v64 row_half_mirror row_mask:0xf bank_mask:0xf bound_ctrl:1
	v_add_f32_dpp v66, v66, v66 row_half_mirror row_mask:0xf bank_mask:0xf bound_ctrl:1
	v_cmp_eq_u32_e32 vcc, 1, v68
	v_add_f32_dpp v60, v60, v60 row_mirror row_mask:0xf bank_mask:0xf bound_ctrl:1
	v_add_f32_dpp v62, v62, v62 row_mirror row_mask:0xf bank_mask:0xf bound_ctrl:1
	v_add_f32_dpp v64, v64, v64 row_mirror row_mask:0xf bank_mask:0xf bound_ctrl:1
	v_add_f32_dpp v66, v66, v66 row_mirror row_mask:0xf bank_mask:0xf bound_ctrl:1
	v_pk_fma_f32 v[94:95], v[130:131], v[60:61], v[94:95] op_sel_hi:[1,0,1] neg_lo:[1,0,0] neg_hi:[1,0,0]
	v_pk_fma_f32 v[92:93], v[132:133], v[60:61], v[92:93] op_sel_hi:[1,0,1] neg_lo:[1,0,0] neg_hi:[1,0,0]
	v_pk_mul_f32 v[238:239], v[130:131], v[62:63] op_sel_hi:[1,0]
	v_pk_mul_f32 v[240:241], v[132:133], v[62:63] op_sel_hi:[1,0]
	v_cndmask_b32_e32 v72, v72, v64, vcc
	v_cndmask_b32_e32 v73, v73, v66, vcc
	v_pk_mul_f32 v[64:65], v[138:139], v[94:95]
	v_pk_fma_f32 v[88:89], v[88:89], v[122:123], v[238:239] neg_lo:[0,0,1] neg_hi:[0,0,1]
	v_pk_fma_f32 v[90:91], v[90:91], v[124:125], v[240:241] neg_lo:[0,0,1] neg_hi:[0,0,1]
	v_pk_fma_f32 v[64:65], v[140:141], v[92:93], v[64:65]
	v_pk_mul_f32 v[66:67], v[138:139], v[88:89]
	v_pk_fma_f32 v[66:67], v[140:141], v[90:91], v[66:67]
	v_add_f32_e32 v64, v64, v65
	v_add_f32_e32 v66, v66, v67
	v_cmp_eq_u32_e32 vcc, 2, v68
	v_add_f32_dpp v64, v64, v64 quad_perm:[1,0,3,2] row_mask:0xf bank_mask:0xf bound_ctrl:1
	v_add_f32_dpp v66, v66, v66 quad_perm:[1,0,3,2] row_mask:0xf bank_mask:0xf bound_ctrl:1
	s_nop 0
	v_add_f32_dpp v64, v64, v64 quad_perm:[2,3,0,1] row_mask:0xf bank_mask:0xf bound_ctrl:1
	v_add_f32_dpp v66, v66, v66 quad_perm:[2,3,0,1] row_mask:0xf bank_mask:0xf bound_ctrl:1
	s_nop 0
	v_add_f32_dpp v64, v64, v64 row_half_mirror row_mask:0xf bank_mask:0xf bound_ctrl:1
	v_add_f32_dpp v66, v66, v66 row_half_mirror row_mask:0xf bank_mask:0xf bound_ctrl:1
	s_nop 0
	v_add_f32_dpp v64, v64, v64 row_mirror row_mask:0xf bank_mask:0xf bound_ctrl:1
	v_add_f32_dpp v66, v66, v66 row_mirror row_mask:0xf bank_mask:0xf bound_ctrl:1
	s_nop 0
	v_cndmask_b32_e32 v72, v72, v64, vcc
	v_cndmask_b32_e32 v73, v73, v66, vcc
	v_or_b32_e32 v79, 16, v101
	v_add_u32_e32 v77, 1, v79
	v_sub_u32_e32 v76, 32, v79
	v_cndmask_b32_e64 v76, v76, v77, s[36:37]
	v_add_u32_e32 v76, s28, v76
	v_ashrrev_i32_e32 v77, 31, v76
	v_lshl_add_u64 v[76:77], s[20:21], 0, v[76:77]
	v_lshlrev_b64 v[76:77], 9, v[76:77]
	v_cvt_pk_bf16_f32 v78, v72, v72
	v_lshl_add_u64 v[76:77], v[84:85], 0, v[76:77]
	global_store_short v[76:77], v78, off
	v_or_b32_e32 v76, s53, v79
	v_mov_b32_e32 v77, s54
	v_cvt_pk_bf16_f32 v79, v73, v73
	v_lshlrev_b64 v[76:77], 9, v[76:77]
	v_lshl_add_u64 v[76:77], v[86:87], 0, v[76:77]
	global_store_short v[76:77], v79, off
	s_branch .LBB0_1436
; template <bool DUAL>
; __device__ __forceinline__ void rwkv_tile(const Params& p, int l, int tile, unsigned char* smem) {
;     ...
; #pragma unroll 2
;       for (int i = 0; i < 32; ++i) {
;         const int inx = (i + 1) & 31;
;         const float4 nw4 = *(const float4*)(rp + inx * 384), nkk4 = *(const float4*)(rp + inx * 384 + 64), nkb4 = *(const float4*)(rp + inx * 384 + 128);
;         const float4 nkd4 = *(const float4*)(rp + inx * 384 + 192), nr4 = *(const float4*)(rp + inx * 384 + 256);
;         const float nv = vp[inx * 384];
;         v2f t = sA * (v2f){kk4.x, kk4.y};
;         t = sB * (v2f){kk4.z, kk4.w} + t;
;         float sa = t.x + t.y, ia = 0.f;
;         if (DUAL) {
;           v2f ti = iA * (v2f){kk4.x, kk4.y};
;           ti = iB * (v2f){kk4.z, kk4.w} + ti;
;           ia = ti.x + ti.y;
;           sa += dppf<0xB1>(sa); ia += dppf<0xB1>(ia);
;           sa += dppf<0x4E>(sa); ia += dppf<0x4E>(ia);
;           sa += dppf<0x141>(sa); ia += dppf<0x141>(ia);
;           sa += dppf<0x140>(sa); ia += dppf<0x140>(ia);
;         } else {
;           sa = sum16(sa);
;         }
;         v2f cA = sA * (v2f){w4.x, w4.y} + (v2f){kd4.x, kd4.y} * v;
;         v2f cB = sB * (v2f){w4.z, w4.w} + (v2f){kd4.z, kd4.w} * v;
;         sA = cA - (v2f){kb4.x, kb4.y} * sa;
;         sB = cB - (v2f){kb4.z, kb4.w} * sa;
;         v2f u = sA * (v2f){r4.x, r4.y};
;         u = sB * (v2f){r4.z, r4.w} + u;
;         float y = u.x + u.y, g = 0.f;
;         if (DUAL) {
;           iA = iA * (v2f){w4.x, w4.y} - (v2f){kb4.x, kb4.y} * ia;
;           iB = iB * (v2f){w4.z, w4.w} - (v2f){kb4.z, kb4.w} * ia;
;           v2f ui = iA * (v2f){r4.x, r4.y};
;           ui = iB * (v2f){r4.z, r4.w} + ui;
;           g = ui.x + ui.y;
;           y += dppf<0xB1>(y); g += dppf<0xB1>(g);
;           y += dppf<0x4E>(y); g += dppf<0x4E>(g);
;           y += dppf<0x141>(y); g += dppf<0x141>(g);
;           y += dppf<0x140>(y); g += dppf<0x140>(g);
;           if (fr == (i & 15)) gkeep = g;
;         } else {
;           y = sum16(y);
;         }
;         if (fr == (i & 15)) ykeep = y;
;         if ((i & 15) == 15) {
;           const int ii = (i & 16) + fr;
;           const int ri = (d == 0) ? ii + 1 : 32 - ii;
;           const int pi = plo - 1 + ri;
;           p.yR[((size_t)d * TOK + rowbase + pi) * 256 + h * 64 + row] = f2bf(ykeep);
.Lrw_du_st0:
	v_mov_b32_e32 v79, v101
	v_add_u32_e32 v77, 1, v79
	v_sub_u32_e32 v76, 32, v79
	v_cndmask_b32_e64 v76, v76, v77, s[36:37]
	v_add_u32_e32 v76, s28, v76
	v_ashrrev_i32_e32 v77, 31, v76
	v_lshl_add_u64 v[76:77], s[20:21], 0, v[76:77]
	v_lshlrev_b64 v[76:77], 9, v[76:77]
	v_cvt_pk_bf16_f32 v78, v72, v72
	v_lshl_add_u64 v[76:77], v[84:85], 0, v[76:77]
	global_store_short v[76:77], v78, off
	v_or_b32_e32 v76, s53, v79
	v_mov_b32_e32 v77, s54
	v_cvt_pk_bf16_f32 v79, v73, v73
	v_lshlrev_b64 v[76:77], 9, v[76:77]
	v_lshl_add_u64 v[76:77], v[86:87], 0, v[76:77]
	global_store_short v[76:77], v79, off
	s_branch .Lrw_du_back
.Lrw_nd_scan:
	v_mov_b32_e32 v72, v99
	v_mov_b32_e32 v73, v100
	v_add_u32_e32 v71, 1, v98
	v_and_b32_e32 v71, 15, v71
	ds_read_b128 v[220:223], v72 offset:25600
	ds_read_b128 v[216:219], v72 offset:25344
	ds_read_b128 v[228:231], v72 offset:26112
	ds_read_b32 v236, v73 offset:26624
	ds_read_b128 v[224:227], v72 offset:25856
	ds_read_b128 v[232:235], v72 offset:26368
	ds_read_b128 v[122:125], v72 offset:27136
	ds_read_b128 v[118:121], v72 offset:26880
	ds_read_b128 v[130:133], v72 offset:27648
	ds_read_b32 v138, v73 offset:28160
	ds_read_b128 v[126:129], v72 offset:27392
	ds_read_b128 v[134:137], v72 offset:27904
	s_mov_b32 s50, 0
.Lrw_nd_loop:
	s_waitcnt lgkmcnt(6)
	v_pk_mul_f32 v[64:65], v[60:61], v[220:221]
	v_pk_fma_f32 v[64:65], v[62:63], v[222:223], v[64:65]
	v_add_f32_e32 v66, v66, v67
	v_add_f32_e32 v64, v64, v65
	v_pk_mul_f32 v[60:61], v[60:61], v[216:217]
	v_pk_mul_f32 v[62:63], v[62:63], v[218:219]
	v_add_f32_dpp v64, v64, v64 quad_perm:[1,0,3,2] row_mask:0xf bank_mask:0xf bound_ctrl:1
	v_add_f32_dpp v66, v66, v66 quad_perm:[1,0,3,2] row_mask:0xf bank_mask:0xf bound_ctrl:1
	v_pk_fma_f32 v[60:61], v[236:237], v[228:229], v[60:61] op_sel_hi:[0,1,1]
	v_add_f32_dpp v64, v64, v64 quad_perm:[2,3,0,1] row_mask:0xf bank_mask:0xf bound_ctrl:1
	v_add_f32_dpp v66, v66, v66 quad_perm:[2,3,0,1] row_mask:0xf bank_mask:0xf bound_ctrl:1
	v_pk_fma_f32 v[62:63], v[236:237], v[230:231], v[62:63] op_sel_hi:[0,1,1]
	v_add_f32_dpp v64, v64, v64 row_half_mirror row_mask:0xf bank_mask:0xf bound_ctrl:1
	v_add_f32_dpp v66, v66, v66 row_half_mirror row_mask:0xf bank_mask:0xf bound_ctrl:1
	v_cmp_eq_u32_e32 vcc, 0, v71
	v_add_f32_dpp v64, v64, v64 row_mirror row_mask:0xf bank_mask:0xf bound_ctrl:1
	v_add_f32_dpp v66, v66, v66 row_mirror row_mask:0xf bank_mask:0xf bound_ctrl:1
	v_pk_fma_f32 v[60:61], v[224:225], v[64:65], v[60:61] op_sel_hi:[1,0,1] neg_lo:[1,0,0] neg_hi:[1,0,0]
	v_pk_fma_f32 v[62:63], v[226:227], v[64:65], v[62:63] op_sel_hi:[1,0,1] neg_lo:[1,0,0] neg_hi:[1,0,0]
	v_cndmask_b32_e32 v70, v70, v66, vcc
	v_pk_mul_f32 v[66:67], v[232:233], v[60:61]
	v_pk_fma_f32 v[66:67], v[234:235], v[62:63], v[66:67]
	ds_read_b128 v[144:147], v72 offset:28672
	ds_read_b128 v[140:143], v72 offset:28416
	ds_read_b128 v[152:155], v72 offset:29184
	ds_read_b32 v160, v73 offset:29696
	ds_read_b128 v[148:151], v72 offset:28928
	ds_read_b128 v[156:159], v72 offset:29440
	s_waitcnt lgkmcnt(6)
	v_pk_mul_f32 v[64:65], v[60:61], v[122:123]
	v_pk_fma_f32 v[64:65], v[62:63], v[124:125], v[64:65]
	v_add_f32_e32 v66, v66, v67
	v_add_f32_e32 v64, v64, v65
	v_pk_mul_f32 v[60:61], v[60:61], v[118:119]
	v_pk_mul_f32 v[62:63], v[62:63], v[120:121]
	v_add_f32_dpp v64, v64, v64 quad_perm:[1,0,3,2] row_mask:0xf bank_mask:0xf bound_ctrl:1
	v_add_f32_dpp v66, v66, v66 quad_perm:[1,0,3,2] row_mask:0xf bank_mask:0xf bound_ctrl:1
	v_pk_fma_f32 v[60:61], v[138:139], v[130:131], v[60:61] op_sel_hi:[0,1,1]
	v_add_f32_dpp v64, v64, v64 quad_perm:[2,3,0,1] row_mask:0xf bank_mask:0xf bound_ctrl:1
	v_add_f32_dpp v66, v66, v66 quad_perm:[2,3,0,1] row_mask:0xf bank_mask:0xf bound_ctrl:1
	v_pk_fma_f32 v[62:63], v[138:139], v[132:133], v[62:63] op_sel_hi:[0,1,1]
	v_add_f32_dpp v64, v64, v64 row_half_mirror row_mask:0xf bank_mask:0xf bound_ctrl:1
	v_add_f32_dpp v66, v66, v66 row_half_mirror row_mask:0xf bank_mask:0xf bound_ctrl:1
	v_cmp_eq_u32_e32 vcc, 1, v71
	v_add_f32_dpp v64, v64, v64 row_mirror row_mask:0xf bank_mask:0xf bound_ctrl:1
	v_add_f32_dpp v66, v66, v66 row_mirror row_mask:0xf bank_mask:0xf bound_ctrl:1
	v_pk_fma_f32 v[60:61], v[126:127], v[64:65], v[60:61] op_sel_hi:[1,0,1] neg_lo:[1,0,0] neg_hi:[1,0,0]
	v_pk_fma_f32 v[62:63], v[128:129], v[64:65], v[62:63] op_sel_hi:[1,0,1] neg_lo:[1,0,0] neg_hi:[1,0,0]
	v_cndmask_b32_e32 v70, v70, v66, vcc
	v_pk_mul_f32 v[66:67], v[134:135], v[60:61]
	v_pk_fma_f32 v[66:67], v[136:137], v[62:63], v[66:67]
	ds_read_b128 v[220:223], v72 offset:30208
	ds_read_b128 v[216:219], v72 offset:29952
	ds_read_b128 v[228:231], v72 offset:30720
	ds_read_b32 v236, v73 offset:31232
	ds_read_b128 v[224:227], v72 offset:30464
	ds_read_b128 v[232:235], v72 offset:30976
	s_waitcnt lgkmcnt(6)
	v_pk_mul_f32 v[64:65], v[60:61], v[144:145]
	v_pk_fma_f32 v[64:65], v[62:63], v[146:147], v[64:65]
	v_add_f32_e32 v66, v66, v67
	v_add_f32_e32 v64, v64, v65
	v_pk_mul_f32 v[60:61], v[60:61], v[140:141]
	v_pk_mul_f32 v[62:63], v[62:63], v[142:143]
	v_add_f32_dpp v64, v64, v64 quad_perm:[1,0,3,2] row_mask:0xf bank_mask:0xf bound_ctrl:1
	v_add_f32_dpp v66, v66, v66 quad_perm:[1,0,3,2] row_mask:0xf bank_mask:0xf bound_ctrl:1
	v_pk_fma_f32 v[60:61], v[160:161], v[152:153], v[60:61] op_sel_hi:[0,1,1]
	v_add_f32_dpp v64, v64, v64 quad_perm:[2,3,0,1] row_mask:0xf bank_mask:0xf bound_ctrl:1
	v_add_f32_dpp v66, v66, v66 quad_perm:[2,3,0,1] row_mask:0xf bank_mask:0xf bound_ctrl:1
	v_pk_fma_f32 v[62:63], v[160:161], v[154:155], v[62:63] op_sel_hi:[0,1,1]
	v_add_f32_dpp v64, v64, v64 row_half_mirror row_mask:0xf bank_mask:0xf bound_ctrl:1
	v_add_f32_dpp v66, v66, v66 row_half_mirror row_mask:0xf bank_mask:0xf bound_ctrl:1
	v_cmp_eq_u32_e32 vcc, 2, v71
	v_add_f32_dpp v64, v64, v64 row_mirror row_mask:0xf bank_mask:0xf bound_ctrl:1
	v_add_f32_dpp v66, v66, v66 row_mirror row_mask:0xf bank_mask:0xf bound_ctrl:1
	v_pk_fma_f32 v[60:61], v[148:149], v[64:65], v[60:61] op_sel_hi:[1,0,1] neg_lo:[1,0,0] neg_hi:[1,0,0]
	v_pk_fma_f32 v[62:63], v[150:151], v[64:65], v[62:63] op_sel_hi:[1,0,1] neg_lo:[1,0,0] neg_hi:[1,0,0]
	v_cndmask_b32_e32 v70, v70, v66, vcc
	v_pk_mul_f32 v[66:67], v[156:157], v[60:61]
	v_pk_fma_f32 v[66:67], v[158:159], v[62:63], v[66:67]
	ds_read_b128 v[122:125], v72 offset:31744
	ds_read_b128 v[118:121], v72 offset:31488
	ds_read_b128 v[130:133], v72 offset:32256
	ds_read_b32 v138, v73 offset:32768
	ds_read_b128 v[126:129], v72 offset:32000
	ds_read_b128 v[134:137], v72 offset:32512
	s_waitcnt lgkmcnt(6)
; template <bool DUAL>
; __device__ __forceinline__ void rwkv_tile(const Params& p, int l, int tile, unsigned char* smem) {
;     ...
; #pragma unroll 2
;       for (int i = 0; i < 32; ++i) {
;         const int inx = (i + 1) & 31;
;         const float4 nw4 = *(const float4*)(rp + inx * 384), nkk4 = *(const float4*)(rp + inx * 384 + 64), nkb4 = *(const float4*)(rp + inx * 384 + 128);
;         const float4 nkd4 = *(const float4*)(rp + inx * 384 + 192), nr4 = *(const float4*)(rp + inx * 384 + 256);
;         const float nv = vp[inx * 384];
;         v2f t = sA * (v2f){kk4.x, kk4.y};
;         t = sB * (v2f){kk4.z, kk4.w} + t;
;         float sa = t.x + t.y, ia = 0.f;
;         if (DUAL) {
;           v2f ti = iA * (v2f){kk4.x, kk4.y};
;           ti = iB * (v2f){kk4.z, kk4.w} + ti;
;           ia = ti.x + ti.y;
;           sa += dppf<0xB1>(sa); ia += dppf<0xB1>(ia);
;           sa += dppf<0x4E>(sa); ia += dppf<0x4E>(ia);
;           sa += dppf<0x141>(sa); ia += dppf<0x141>(ia);
;           sa += dppf<0x140>(sa); ia += dppf<0x140>(ia);
;         } else {
;           sa = sum16(sa);
;         }
;         v2f cA = sA * (v2f){w4.x, w4.y} + (v2f){kd4.x, kd4.y} * v;
;         v2f cB = sB * (v2f){w4.z, w4.w} + (v2f){kd4.z, kd4.w} * v;
;         sA = cA - (v2f){kb4.x, kb4.y} * sa;
;         sB = cB - (v2f){kb4.z, kb4.w} * sa;
;         v2f u = sA * (v2f){r4.x, r4.y};
;         u = sB * (v2f){r4.z, r4.w} + u;
;         float y = u.x + u.y, g = 0.f;
;         if (DUAL) {
;           iA = iA * (v2f){w4.x, w4.y} - (v2f){kb4.x, kb4.y} * ia;
;           iB = iB * (v2f){w4.z, w4.w} - (v2f){kb4.z, kb4.w} * ia;
;           v2f ui = iA * (v2f){r4.x, r4.y};
;           ui = iB * (v2f){r4.z, r4.w} + ui;
;           g = ui.x + ui.y;
;           y += dppf<0xB1>(y); g += dppf<0xB1>(g);
;           y += dppf<0x4E>(y); g += dppf<0x4E>(g);
;           y += dppf<0x141>(y); g += dppf<0x141>(g);
;           y += dppf<0x140>(y); g += dppf<0x140>(g);
;           if (fr == (i & 15)) gkeep = g;
;         } else {
;           y = sum16(y);
;         }
;         if (fr == (i & 15)) ykeep = y;
	v_pk_mul_f32 v[64:65], v[60:61], v[220:221]
	v_pk_fma_f32 v[64:65], v[62:63], v[222:223], v[64:65]
	v_add_f32_e32 v66, v66, v67
	v_add_f32_e32 v64, v64, v65
	v_pk_mul_f32 v[60:61], v[60:61], v[216:217]
	v_pk_mul_f32 v[62:63], v[62:63], v[218:219]
	v_add_f32_dpp v64, v64, v64 quad_perm:[1,0,3,2] row_mask:0xf bank_mask:0xf bound_ctrl:1
	v_add_f32_dpp v66, v66, v66 quad_perm:[1,0,3,2] row_mask:0xf bank_mask:0xf bound_ctrl:1
	v_pk_fma_f32 v[60:61], v[236:237], v[228:229], v[60:61] op_sel_hi:[0,1,1]
	v_add_f32_dpp v64, v64, v64 quad_perm:[2,3,0,1] row_mask:0xf bank_mask:0xf bound_ctrl:1
	v_add_f32_dpp v66, v66, v66 quad_perm:[2,3,0,1] row_mask:0xf bank_mask:0xf bound_ctrl:1
	v_pk_fma_f32 v[62:63], v[236:237], v[230:231], v[62:63] op_sel_hi:[0,1,1]
	v_add_f32_dpp v64, v64, v64 row_half_mirror row_mask:0xf bank_mask:0xf bound_ctrl:1
	v_add_f32_dpp v66, v66, v66 row_half_mirror row_mask:0xf bank_mask:0xf bound_ctrl:1
	v_cmp_eq_u32_e32 vcc, 3, v71
	v_add_f32_dpp v64, v64, v64 row_mirror row_mask:0xf bank_mask:0xf bound_ctrl:1
	v_add_f32_dpp v66, v66, v66 row_mirror row_mask:0xf bank_mask:0xf bound_ctrl:1
	v_pk_fma_f32 v[60:61], v[224:225], v[64:65], v[60:61] op_sel_hi:[1,0,1] neg_lo:[1,0,0] neg_hi:[1,0,0]
	v_pk_fma_f32 v[62:63], v[226:227], v[64:65], v[62:63] op_sel_hi:[1,0,1] neg_lo:[1,0,0] neg_hi:[1,0,0]
	v_cndmask_b32_e32 v70, v70, v66, vcc
	v_pk_mul_f32 v[66:67], v[232:233], v[60:61]
	v_pk_fma_f32 v[66:67], v[234:235], v[62:63], v[66:67]
	ds_read_b128 v[144:147], v72 offset:33280
	ds_read_b128 v[140:143], v72 offset:33024
	ds_read_b128 v[152:155], v72 offset:33792
	ds_read_b32 v160, v73 offset:34304
	ds_read_b128 v[148:151], v72 offset:33536
	ds_read_b128 v[156:159], v72 offset:34048
	s_waitcnt lgkmcnt(6)
	v_pk_mul_f32 v[64:65], v[60:61], v[122:123]
	v_pk_fma_f32 v[64:65], v[62:63], v[124:125], v[64:65]
	v_add_f32_e32 v66, v66, v67
	v_add_f32_e32 v64, v64, v65
	v_pk_mul_f32 v[60:61], v[60:61], v[118:119]
	v_pk_mul_f32 v[62:63], v[62:63], v[120:121]
	v_add_f32_dpp v64, v64, v64 quad_perm:[1,0,3,2] row_mask:0xf bank_mask:0xf bound_ctrl:1
	v_add_f32_dpp v66, v66, v66 quad_perm:[1,0,3,2] row_mask:0xf bank_mask:0xf bound_ctrl:1
	v_pk_fma_f32 v[60:61], v[138:139], v[130:131], v[60:61] op_sel_hi:[0,1,1]
	v_add_f32_dpp v64, v64, v64 quad_perm:[2,3,0,1] row_mask:0xf bank_mask:0xf bound_ctrl:1
	v_add_f32_dpp v66, v66, v66 quad_perm:[2,3,0,1] row_mask:0xf bank_mask:0xf bound_ctrl:1
	v_pk_fma_f32 v[62:63], v[138:139], v[132:133], v[62:63] op_sel_hi:[0,1,1]
	v_add_f32_dpp v64, v64, v64 row_half_mirror row_mask:0xf bank_mask:0xf bound_ctrl:1
	v_add_f32_dpp v66, v66, v66 row_half_mirror row_mask:0xf bank_mask:0xf bound_ctrl:1
	v_cmp_eq_u32_e32 vcc, 4, v71
	v_add_f32_dpp v64, v64, v64 row_mirror row_mask:0xf bank_mask:0xf bound_ctrl:1
	v_add_f32_dpp v66, v66, v66 row_mirror row_mask:0xf bank_mask:0xf bound_ctrl:1
	v_pk_fma_f32 v[60:61], v[126:127], v[64:65], v[60:61] op_sel_hi:[1,0,1] neg_lo:[1,0,0] neg_hi:[1,0,0]
	v_pk_fma_f32 v[62:63], v[128:129], v[64:65], v[62:63] op_sel_hi:[1,0,1] neg_lo:[1,0,0] neg_hi:[1,0,0]
	v_cndmask_b32_e32 v70, v70, v66, vcc
	s_cmp_eq_u32 s50, 2
	s_cbranch_scc1 .Lrw_nd_st0
; template <bool DUAL>
; __device__ __forceinline__ void rwkv_tile(const Params& p, int l, int tile, unsigned char* smem) {
;     ...
; #pragma unroll 2
;       for (int i = 0; i < 32; ++i) {
;         const int inx = (i + 1) & 31;
;         const float4 nw4 = *(const float4*)(rp + inx * 384), nkk4 = *(const float4*)(rp + inx * 384 + 64), nkb4 = *(const float4*)(rp + inx * 384 + 128);
;         const float4 nkd4 = *(const float4*)(rp + inx * 384 + 192), nr4 = *(const float4*)(rp + inx * 384 + 256);
;         const float nv = vp[inx * 384];
;         v2f t = sA * (v2f){kk4.x, kk4.y};
;         t = sB * (v2f){kk4.z, kk4.w} + t;
;         float sa = t.x + t.y, ia = 0.f;
;         if (DUAL) {
;           v2f ti = iA * (v2f){kk4.x, kk4.y};
;           ti = iB * (v2f){kk4.z, kk4.w} + ti;
;           ia = ti.x + ti.y;
;           sa += dppf<0xB1>(sa); ia += dppf<0xB1>(ia);
;           sa += dppf<0x4E>(sa); ia += dppf<0x4E>(ia);
;           sa += dppf<0x141>(sa); ia += dppf<0x141>(ia);
;           sa += dppf<0x140>(sa); ia += dppf<0x140>(ia);
;         } else {
;           sa = sum16(sa);
;         }
;         v2f cA = sA * (v2f){w4.x, w4.y} + (v2f){kd4.x, kd4.y} * v;
;         v2f cB = sB * (v2f){w4.z, w4.w} + (v2f){kd4.z, kd4.w} * v;
;         sA = cA - (v2f){kb4.x, kb4.y} * sa;
;         sB = cB - (v2f){kb4.z, kb4.w} * sa;
;         v2f u = sA * (v2f){r4.x, r4.y};
;         u = sB * (v2f){r4.z, r4.w} + u;
;         float y = u.x + u.y, g = 0.f;
;         if (DUAL) {
;           iA = iA * (v2f){w4.x, w4.y} - (v2f){kb4.x, kb4.y} * ia;
;           iB = iB * (v2f){w4.z, w4.w} - (v2f){kb4.z, kb4.w} * ia;
;           v2f ui = iA * (v2f){r4.x, r4.y};
;           ui = iB * (v2f){r4.z, r4.w} + ui;
;           g = ui.x + ui.y;
;           y += dppf<0xB1>(y); g += dppf<0xB1>(g);
;           y += dppf<0x4E>(y); g += dppf<0x4E>(g);
;           y += dppf<0x141>(y); g += dppf<0x141>(g);
;           y += dppf<0x140>(y); g += dppf<0x140>(g);
;           if (fr == (i & 15)) gkeep = g;
;         } else {
;           y = sum16(y);
;         }
;         if (fr == (i & 15)) ykeep = y;
;         if ((i & 15) == 15) {
;           const int ii = (i & 16) + fr;
;           const int ri = (d == 0) ? ii + 1 : 32 - ii;
;           const int pi = plo - 1 + ri;
;           p.yR[((size_t)d * TOK + rowbase + pi) * 256 + h * 64 + row] = f2bf(ykeep);
.Lrw_nd_back:
	v_pk_mul_f32 v[66:67], v[134:135], v[60:61]
	v_pk_fma_f32 v[66:67], v[136:137], v[62:63], v[66:67]
	ds_read_b128 v[220:223], v72 offset:34816
	ds_read_b128 v[216:219], v72 offset:34560
	ds_read_b128 v[228:231], v72 offset:35328
	ds_read_b32 v236, v73 offset:35840
	ds_read_b128 v[224:227], v72 offset:35072
	ds_read_b128 v[232:235], v72 offset:35584
	s_waitcnt lgkmcnt(6)
	v_pk_mul_f32 v[64:65], v[60:61], v[144:145]
	v_pk_fma_f32 v[64:65], v[62:63], v[146:147], v[64:65]
	v_add_f32_e32 v66, v66, v67
	v_add_f32_e32 v64, v64, v65
	v_pk_mul_f32 v[60:61], v[60:61], v[140:141]
	v_pk_mul_f32 v[62:63], v[62:63], v[142:143]
	v_add_f32_dpp v64, v64, v64 quad_perm:[1,0,3,2] row_mask:0xf bank_mask:0xf bound_ctrl:1
	v_add_f32_dpp v66, v66, v66 quad_perm:[1,0,3,2] row_mask:0xf bank_mask:0xf bound_ctrl:1
	v_pk_fma_f32 v[60:61], v[160:161], v[152:153], v[60:61] op_sel_hi:[0,1,1]
	v_add_f32_dpp v64, v64, v64 quad_perm:[2,3,0,1] row_mask:0xf bank_mask:0xf bound_ctrl:1
	v_add_f32_dpp v66, v66, v66 quad_perm:[2,3,0,1] row_mask:0xf bank_mask:0xf bound_ctrl:1
	v_pk_fma_f32 v[62:63], v[160:161], v[154:155], v[62:63] op_sel_hi:[0,1,1]
	v_add_f32_dpp v64, v64, v64 row_half_mirror row_mask:0xf bank_mask:0xf bound_ctrl:1
	v_add_f32_dpp v66, v66, v66 row_half_mirror row_mask:0xf bank_mask:0xf bound_ctrl:1
	v_cmp_eq_u32_e32 vcc, 5, v71
	v_add_f32_dpp v64, v64, v64 row_mirror row_mask:0xf bank_mask:0xf bound_ctrl:1
	v_add_f32_dpp v66, v66, v66 row_mirror row_mask:0xf bank_mask:0xf bound_ctrl:1
	v_pk_fma_f32 v[60:61], v[148:149], v[64:65], v[60:61] op_sel_hi:[1,0,1] neg_lo:[1,0,0] neg_hi:[1,0,0]
	v_pk_fma_f32 v[62:63], v[150:151], v[64:65], v[62:63] op_sel_hi:[1,0,1] neg_lo:[1,0,0] neg_hi:[1,0,0]
	v_cndmask_b32_e32 v70, v70, v66, vcc
	v_pk_mul_f32 v[66:67], v[156:157], v[60:61]
	v_pk_fma_f32 v[66:67], v[158:159], v[62:63], v[66:67]
	ds_read_b128 v[122:125], v72 offset:36352
	ds_read_b128 v[118:121], v72 offset:36096
	ds_read_b128 v[130:133], v72 offset:36864
	ds_read_b32 v138, v73 offset:37376
	ds_read_b128 v[126:129], v72 offset:36608
	ds_read_b128 v[134:137], v72 offset:37120
	v_add_u32_e32 v72, 0x2400, v72
	v_add_u32_e32 v73, 0x2400, v73
	v_add_u32_e32 v71, -6, v71
	v_and_b32_e32 v71, 15, v71
	s_add_i32 s50, s50, 1
	s_cmp_lg_u32 s50, 5
	s_cbranch_scc1 .Lrw_nd_loop
	s_waitcnt lgkmcnt(6)
	v_pk_mul_f32 v[64:65], v[60:61], v[220:221]
	v_pk_fma_f32 v[64:65], v[62:63], v[222:223], v[64:65]
	v_add_f32_e32 v66, v66, v67
	v_add_f32_e32 v64, v64, v65
	v_pk_mul_f32 v[60:61], v[60:61], v[216:217]
	v_pk_mul_f32 v[62:63], v[62:63], v[218:219]
	v_add_f32_dpp v64, v64, v64 quad_perm:[1,0,3,2] row_mask:0xf bank_mask:0xf bound_ctrl:1
	v_add_f32_dpp v66, v66, v66 quad_perm:[1,0,3,2] row_mask:0xf bank_mask:0xf bound_ctrl:1
	v_pk_fma_f32 v[60:61], v[236:237], v[228:229], v[60:61] op_sel_hi:[0,1,1]
	v_add_f32_dpp v64, v64, v64 quad_perm:[2,3,0,1] row_mask:0xf bank_mask:0xf bound_ctrl:1
	v_add_f32_dpp v66, v66, v66 quad_perm:[2,3,0,1] row_mask:0xf bank_mask:0xf bound_ctrl:1
	v_pk_fma_f32 v[62:63], v[236:237], v[230:231], v[62:63] op_sel_hi:[0,1,1]
	v_add_f32_dpp v64, v64, v64 row_half_mirror row_mask:0xf bank_mask:0xf bound_ctrl:1
	v_add_f32_dpp v66, v66, v66 row_half_mirror row_mask:0xf bank_mask:0xf bound_ctrl:1
	v_cmp_eq_u32_e32 vcc, 0, v71
	v_add_f32_dpp v64, v64, v64 row_mirror row_mask:0xf bank_mask:0xf bound_ctrl:1
	v_add_f32_dpp v66, v66, v66 row_mirror row_mask:0xf bank_mask:0xf bound_ctrl:1
	v_pk_fma_f32 v[60:61], v[224:225], v[64:65], v[60:61] op_sel_hi:[1,0,1] neg_lo:[1,0,0] neg_hi:[1,0,0]
	v_pk_fma_f32 v[62:63], v[226:227], v[64:65], v[62:63] op_sel_hi:[1,0,1] neg_lo:[1,0,0] neg_hi:[1,0,0]
	v_cndmask_b32_e32 v70, v70, v66, vcc
	v_pk_mul_f32 v[66:67], v[232:233], v[60:61]
	v_pk_fma_f32 v[66:67], v[234:235], v[62:63], v[66:67]
	s_waitcnt lgkmcnt(0)
	v_pk_mul_f32 v[64:65], v[60:61], v[122:123]
	v_pk_fma_f32 v[64:65], v[62:63], v[124:125], v[64:65]
	v_add_f32_e32 v66, v66, v67
	v_add_f32_e32 v64, v64, v65
	v_pk_mul_f32 v[60:61], v[60:61], v[118:119]
	v_pk_mul_f32 v[62:63], v[62:63], v[120:121]
	v_add_f32_dpp v64, v64, v64 quad_perm:[1,0,3,2] row_mask:0xf bank_mask:0xf bound_ctrl:1
	v_add_f32_dpp v66, v66, v66 quad_perm:[1,0,3,2] row_mask:0xf bank_mask:0xf bound_ctrl:1
	v_pk_fma_f32 v[60:61], v[138:139], v[130:131], v[60:61] op_sel_hi:[0,1,1]
	v_add_f32_dpp v64, v64, v64 quad_perm:[2,3,0,1] row_mask:0xf bank_mask:0xf bound_ctrl:1
	v_add_f32_dpp v66, v66, v66 quad_perm:[2,3,0,1] row_mask:0xf bank_mask:0xf bound_ctrl:1
	v_pk_fma_f32 v[62:63], v[138:139], v[132:133], v[62:63] op_sel_hi:[0,1,1]
	v_add_f32_dpp v64, v64, v64 row_half_mirror row_mask:0xf bank_mask:0xf bound_ctrl:1
	v_add_f32_dpp v66, v66, v66 row_half_mirror row_mask:0xf bank_mask:0xf bound_ctrl:1
	v_cmp_eq_u32_e32 vcc, 1, v71
	v_add_f32_dpp v64, v64, v64 row_mirror row_mask:0xf bank_mask:0xf bound_ctrl:1
	v_add_f32_dpp v66, v66, v66 row_mirror row_mask:0xf bank_mask:0xf bound_ctrl:1
	v_pk_fma_f32 v[60:61], v[126:127], v[64:65], v[60:61] op_sel_hi:[1,0,1] neg_lo:[1,0,0] neg_hi:[1,0,0]
	v_pk_fma_f32 v[62:63], v[128:129], v[64:65], v[62:63] op_sel_hi:[1,0,1] neg_lo:[1,0,0] neg_hi:[1,0,0]
	v_cndmask_b32_e32 v70, v70, v66, vcc
	v_pk_mul_f32 v[66:67], v[134:135], v[60:61]
	v_pk_fma_f32 v[66:67], v[136:137], v[62:63], v[66:67]
	v_add_f32_e32 v66, v66, v67
	v_cmp_eq_u32_e32 vcc, 2, v71
	s_nop 1
	v_add_f32_dpp v66, v66, v66 quad_perm:[1,0,3,2] row_mask:0xf bank_mask:0xf bound_ctrl:1
	s_nop 1
	v_add_f32_dpp v66, v66, v66 quad_perm:[2,3,0,1] row_mask:0xf bank_mask:0xf bound_ctrl:1
	s_nop 1
	v_add_f32_dpp v66, v66, v66 row_half_mirror row_mask:0xf bank_mask:0xf bound_ctrl:1
	s_nop 1
	v_add_f32_dpp v66, v66, v66 row_mirror row_mask:0xf bank_mask:0xf bound_ctrl:1
	v_cndmask_b32_e32 v70, v70, v66, vcc
	v_or_b32_e32 v77, 16, v98
	v_add_u32_e32 v75, 1, v77
	v_sub_u32_e32 v74, 32, v77
	v_cndmask_b32_e64 v74, v74, v75, s[36:37]
	v_add_u32_e32 v74, s28, v74
	v_ashrrev_i32_e32 v75, 31, v74
	v_lshl_add_u64 v[74:75], s[20:21], 0, v[74:75]
	v_lshlrev_b64 v[74:75], 9, v[74:75]
	v_cvt_pk_bf16_f32 v76, v70, v70
	v_lshl_add_u64 v[74:75], v[90:91], 0, v[74:75]
	global_store_short v[74:75], v76, off
	s_branch .LBB0_1491
.Lrw_nd_st0:
	v_mov_b32_e32 v77, v98
	v_add_u32_e32 v75, 1, v77
	v_sub_u32_e32 v74, 32, v77
	v_cndmask_b32_e64 v74, v74, v75, s[36:37]
	v_add_u32_e32 v74, s28, v74
	v_ashrrev_i32_e32 v75, 31, v74
	v_lshl_add_u64 v[74:75], s[20:21], 0, v[74:75]
	v_lshlrev_b64 v[74:75], 9, v[74:75]
	v_cvt_pk_bf16_f32 v76, v70, v70
	v_lshl_add_u64 v[74:75], v[90:91], 0, v[74:75]
	global_store_short v[74:75], v76, off
	s_branch .Lrw_nd_back
